# np7 + wave 0-3 priority raised only inside each tile's K loop, equal priority in tile epilogues
# baseline (speedup 1.0000x reference)
.LBB0_217:
	s_add_u32 s42, s42, 0x40080
	s_addc_u32 s43, s43, 0
	s_add_u32 s27, s48, 0x100
	v_mov_b32_e32 v2, 0
	s_addc_u32 s31, s49, 0
	s_mov_b32 s44, -2
	v_mov_b32_e32 v3, v2
	v_mov_b32_e32 v4, v2
	v_mov_b32_e32 v5, v2
	v_mov_b32_e32 v6, v2
	v_mov_b32_e32 v7, v2
	v_mov_b32_e32 v8, v2
	v_mov_b32_e32 v9, v2
	v_mov_b32_e32 v10, v2
	v_mov_b32_e32 v11, v2
	v_mov_b32_e32 v12, v2
	v_mov_b32_e32 v13, v2
	v_mov_b32_e32 v14, v2
	v_mov_b32_e32 v15, v2
	v_mov_b32_e32 v16, v2
	v_mov_b32_e32 v17, v2
	v_mov_b32_e32 v26, v2
	v_mov_b32_e32 v27, v2
	v_mov_b32_e32 v28, v2
	v_mov_b32_e32 v29, v2
	v_mov_b32_e32 v30, v2
	v_mov_b32_e32 v31, v2
	v_mov_b32_e32 v32, v2
	v_mov_b32_e32 v33, v2
	v_mov_b32_e32 v42, v2
	v_mov_b32_e32 v43, v2
	v_mov_b32_e32 v44, v2
	v_mov_b32_e32 v45, v2
	v_mov_b32_e32 v46, v2
	v_mov_b32_e32 v47, v2
	v_mov_b32_e32 v48, v2
	v_mov_b32_e32 v49, v2
	v_mov_b32_e32 v18, v2
	v_mov_b32_e32 v19, v2
	v_mov_b32_e32 v20, v2
	v_mov_b32_e32 v21, v2
	v_mov_b32_e32 v22, v2
	v_mov_b32_e32 v23, v2
	v_mov_b32_e32 v24, v2
	v_mov_b32_e32 v25, v2
	v_mov_b32_e32 v34, v2
	v_mov_b32_e32 v35, v2
	v_mov_b32_e32 v36, v2
	v_mov_b32_e32 v37, v2
	v_mov_b32_e32 v38, v2
	v_mov_b32_e32 v39, v2
	v_mov_b32_e32 v40, v2
	v_mov_b32_e32 v41, v2
	v_mov_b32_e32 v50, v2
	v_mov_b32_e32 v51, v2
	v_mov_b32_e32 v52, v2
	v_mov_b32_e32 v53, v2
	v_mov_b32_e32 v54, v2
	v_mov_b32_e32 v55, v2
	v_mov_b32_e32 v56, v2
	v_mov_b32_e32 v57, v2
	v_mov_b32_e32 v58, v2
	v_mov_b32_e32 v59, v2
	v_mov_b32_e32 v60, v2
	v_mov_b32_e32 v61, v2
	v_mov_b32_e32 v62, v2
	v_mov_b32_e32 v63, v2
	v_mov_b32_e32 v64, v2
	v_mov_b32_e32 v65, v2
	v_mov_b32_e32 v66, v2
	v_mov_b32_e32 v67, v2
	v_mov_b32_e32 v68, v2
	v_mov_b32_e32 v69, v2
	v_mov_b32_e32 v70, v2
	v_mov_b32_e32 v71, v2
	v_mov_b32_e32 v72, v2
	v_mov_b32_e32 v73, v2
	v_mov_b32_e32 v74, v2
	v_mov_b32_e32 v75, v2
	v_mov_b32_e32 v76, v2
	v_mov_b32_e32 v77, v2
	v_mov_b32_e32 v78, v2
	v_mov_b32_e32 v79, v2
	v_mov_b32_e32 v80, v2
	v_mov_b32_e32 v81, v2
	v_mov_b32_e32 v90, v2
	v_mov_b32_e32 v91, v2
	v_mov_b32_e32 v92, v2
	v_mov_b32_e32 v93, v2
	v_mov_b32_e32 v94, v2
	v_mov_b32_e32 v95, v2
	v_mov_b32_e32 v96, v2
	v_mov_b32_e32 v97, v2
	v_mov_b32_e32 v106, v2
	v_mov_b32_e32 v107, v2
	v_mov_b32_e32 v108, v2
	v_mov_b32_e32 v109, v2
	v_mov_b32_e32 v110, v2
	v_mov_b32_e32 v111, v2
	v_mov_b32_e32 v112, v2
	v_mov_b32_e32 v113, v2
	v_mov_b32_e32 v82, v2
	v_mov_b32_e32 v83, v2
	v_mov_b32_e32 v84, v2
	v_mov_b32_e32 v85, v2
	v_mov_b32_e32 v86, v2
	v_mov_b32_e32 v87, v2
	v_mov_b32_e32 v88, v2
	v_mov_b32_e32 v89, v2
	v_mov_b32_e32 v98, v2
	v_mov_b32_e32 v99, v2
	v_mov_b32_e32 v100, v2
	v_mov_b32_e32 v101, v2
	v_mov_b32_e32 v102, v2
	v_mov_b32_e32 v103, v2
	v_mov_b32_e32 v104, v2
	v_mov_b32_e32 v105, v2
	v_mov_b32_e32 v114, v2
	v_mov_b32_e32 v115, v2
	v_mov_b32_e32 v116, v2
	v_mov_b32_e32 v117, v2
	v_mov_b32_e32 v118, v2
	v_mov_b32_e32 v119, v2
	v_mov_b32_e32 v120, v2
	v_mov_b32_e32 v121, v2
	v_mov_b32_e32 v122, v2
	v_mov_b32_e32 v123, v2
	v_mov_b32_e32 v124, v2
	v_mov_b32_e32 v125, v2
	v_mov_b32_e32 v126, v2
	v_mov_b32_e32 v127, v2
	v_mov_b32_e32 v128, v2
	v_mov_b32_e32 v129, v2
	v_cmp_gt_u32_e32 vcc, 0x100, v1
	s_cbranch_vccz .Lkprio_1
	s_setprio 1
.Lkprio_1:
.LBB0_218:
	ds_read_b128 v[152:155], v149
	ds_read_b128 v[156:159], v149 offset:1024
	ds_read_b128 v[160:163], v149 offset:2048
	ds_read_b128 v[164:167], v149 offset:3072
	ds_read_b128 v[168:171], v150
	ds_read_b128 v[172:175], v150 offset:1024
	ds_read_b128 v[176:179], v150 offset:2048
	ds_read_b128 v[180:183], v150 offset:3072
	s_add_u32 s45, s42, 0xfffc0080
	s_addc_u32 s48, s43, -1
	s_cmp_eq_u32 s44, 12
	s_cselect_b32 s57, s39, s48
	s_cselect_b32 s56, s38, s45
	s_cselect_b32 s49, s41, s31
	s_cselect_b32 s48, s40, s27
	v_lshl_add_u64 v[216:217], s[42:43], 0, v[138:139]
	s_add_i32 m0, s29, 0xc000
	ds_read_b128 v[184:187], v151
	ds_read_b128 v[188:191], v151 offset:1024
	ds_read_b128 v[192:195], v151 offset:2048
	ds_read_b128 v[196:199], v151 offset:3072
	ds_read_b128 v[200:203], v151 offset:4096
	ds_read_b128 v[204:207], v151 offset:5120
	ds_read_b128 v[208:211], v151 offset:6144
	ds_read_b128 v[212:215], v151 offset:7168
	global_load_lds_dwordx4 v[216:217], off
	v_lshl_add_u64 v[216:217], s[42:43], 0, v[140:141]
	s_add_i32 m0, s29, 0xe000
	s_nop 0
	global_load_lds_dwordx4 v[216:217], off
	s_waitcnt vmcnt(8)
	s_waitcnt lgkmcnt(0)
	s_barrier
	s_waitcnt lgkmcnt(0)
	v_mfma_f32_16x16x32_bf16 v[126:129], v[152:155], v[184:187], v[126:129]
	v_mfma_f32_16x16x32_bf16 v[122:125], v[160:163], v[184:187], v[122:125]
	v_mfma_f32_16x16x32_bf16 v[118:121], v[152:155], v[192:195], v[118:121]
	v_mfma_f32_16x16x32_bf16 v[114:117], v[160:163], v[192:195], v[114:117]
	v_mfma_f32_16x16x32_bf16 v[102:105], v[152:155], v[200:203], v[102:105]
	v_mfma_f32_16x16x32_bf16 v[98:101], v[160:163], v[200:203], v[98:101]
	v_mfma_f32_16x16x32_bf16 v[86:89], v[152:155], v[208:211], v[86:89]
	v_mfma_f32_16x16x32_bf16 v[82:85], v[160:163], v[208:211], v[82:85]
	v_mfma_f32_16x16x32_bf16 v[126:129], v[156:159], v[188:191], v[126:129]
	v_mfma_f32_16x16x32_bf16 v[122:125], v[164:167], v[188:191], v[122:125]
	v_mfma_f32_16x16x32_bf16 v[118:121], v[156:159], v[196:199], v[118:121]
	v_mfma_f32_16x16x32_bf16 v[114:117], v[164:167], v[196:199], v[114:117]
	v_mfma_f32_16x16x32_bf16 v[102:105], v[156:159], v[204:207], v[102:105]
	v_mfma_f32_16x16x32_bf16 v[98:101], v[164:167], v[204:207], v[98:101]
	v_mfma_f32_16x16x32_bf16 v[86:89], v[156:159], v[212:215], v[86:89]
	v_mfma_f32_16x16x32_bf16 v[82:85], v[164:167], v[212:215], v[82:85]
	v_mfma_f32_16x16x32_bf16 v[110:113], v[168:171], v[184:187], v[110:113]
	v_mfma_f32_16x16x32_bf16 v[106:109], v[176:179], v[184:187], v[106:109]
	v_mfma_f32_16x16x32_bf16 v[94:97], v[168:171], v[192:195], v[94:97]
	v_mfma_f32_16x16x32_bf16 v[90:93], v[176:179], v[192:195], v[90:93]
	v_mfma_f32_16x16x32_bf16 v[78:81], v[168:171], v[200:203], v[78:81]
	v_mfma_f32_16x16x32_bf16 v[74:77], v[176:179], v[200:203], v[74:77]
	v_mfma_f32_16x16x32_bf16 v[70:73], v[168:171], v[208:211], v[70:73]
	v_mfma_f32_16x16x32_bf16 v[66:69], v[176:179], v[208:211], v[66:69]
	v_mfma_f32_16x16x32_bf16 v[110:113], v[172:175], v[188:191], v[110:113]
	v_mfma_f32_16x16x32_bf16 v[106:109], v[180:183], v[188:191], v[106:109]
	v_mfma_f32_16x16x32_bf16 v[94:97], v[172:175], v[196:199], v[94:97]
	v_mfma_f32_16x16x32_bf16 v[90:93], v[180:183], v[196:199], v[90:93]
	v_mfma_f32_16x16x32_bf16 v[78:81], v[172:175], v[204:207], v[78:81]
	v_mfma_f32_16x16x32_bf16 v[74:77], v[180:183], v[204:207], v[74:77]
	v_mfma_f32_16x16x32_bf16 v[70:73], v[172:175], v[212:215], v[70:73]
	v_mfma_f32_16x16x32_bf16 v[66:69], v[180:183], v[212:215], v[66:69]
	s_barrier
	s_add_i32 s45, s80, s59
	v_lshl_add_u64 v[216:217], s[48:49], 0, v[132:133]
	s_mov_b32 m0, s45
	ds_read_b128 v[184:187], v151 offset:16384
	ds_read_b128 v[188:191], v151 offset:17408
	ds_read_b128 v[192:195], v151 offset:18432
	ds_read_b128 v[196:199], v151 offset:19456
	ds_read_b128 v[200:203], v151 offset:20480
	ds_read_b128 v[204:207], v151 offset:21504
	ds_read_b128 v[208:211], v151 offset:22528
	ds_read_b128 v[212:215], v151 offset:23552
	global_load_lds_dwordx4 v[216:217], off
	s_add_i32 m0, s45, 0x2000
	s_add_u32 s92, s48, 0x40000
	v_lshl_add_u64 v[218:219], s[48:49], 0, v[136:137]
	s_addc_u32 s93, s49, 0
	s_add_i32 s45, s81, s59
	global_load_lds_dwordx4 v[218:219], off
	v_lshl_add_u64 v[220:221], s[92:93], 0, v[132:133]
	s_mov_b32 m0, s45
	v_lshl_add_u64 v[222:223], s[56:57], 0, v[134:135]
	global_load_lds_dwordx4 v[220:221], off
	v_lshl_add_u64 v[220:221], s[92:93], 0, v[136:137]
	s_add_i32 m0, s45, 0x2000
	s_nop 0
	global_load_lds_dwordx4 v[220:221], off
	v_lshl_add_u64 v[220:221], s[56:57], 0, v[130:131]
	s_mov_b32 m0, s29
	s_nop 0
	global_load_lds_dwordx4 v[220:221], off
	s_mov_b32 m0, s62
	s_nop 0
	global_load_lds_dwordx4 v[222:223], off
	s_waitcnt vmcnt(8)
	s_waitcnt lgkmcnt(0)
	s_barrier
	s_waitcnt lgkmcnt(0)
	v_mfma_f32_16x16x32_bf16 v[62:65], v[152:155], v[184:187], v[62:65]
	v_mfma_f32_16x16x32_bf16 v[58:61], v[160:163], v[184:187], v[58:61]
	v_mfma_f32_16x16x32_bf16 v[54:57], v[152:155], v[192:195], v[54:57]
	v_mfma_f32_16x16x32_bf16 v[50:53], v[160:163], v[192:195], v[50:53]
	v_mfma_f32_16x16x32_bf16 v[38:41], v[152:155], v[200:203], v[38:41]
	v_mfma_f32_16x16x32_bf16 v[34:37], v[160:163], v[200:203], v[34:37]
	v_mfma_f32_16x16x32_bf16 v[22:25], v[152:155], v[208:211], v[22:25]
	v_mfma_f32_16x16x32_bf16 v[18:21], v[160:163], v[208:211], v[18:21]
	v_mfma_f32_16x16x32_bf16 v[62:65], v[156:159], v[188:191], v[62:65]
	v_mfma_f32_16x16x32_bf16 v[58:61], v[164:167], v[188:191], v[58:61]
	v_mfma_f32_16x16x32_bf16 v[54:57], v[156:159], v[196:199], v[54:57]
	v_mfma_f32_16x16x32_bf16 v[50:53], v[164:167], v[196:199], v[50:53]
	v_mfma_f32_16x16x32_bf16 v[38:41], v[156:159], v[204:207], v[38:41]
	v_mfma_f32_16x16x32_bf16 v[34:37], v[164:167], v[204:207], v[34:37]
	v_mfma_f32_16x16x32_bf16 v[22:25], v[156:159], v[212:215], v[22:25]
	v_mfma_f32_16x16x32_bf16 v[18:21], v[164:167], v[212:215], v[18:21]
	v_mfma_f32_16x16x32_bf16 v[46:49], v[168:171], v[184:187], v[46:49]
	v_mfma_f32_16x16x32_bf16 v[42:45], v[176:179], v[184:187], v[42:45]
	v_mfma_f32_16x16x32_bf16 v[30:33], v[168:171], v[192:195], v[30:33]
	v_mfma_f32_16x16x32_bf16 v[26:29], v[176:179], v[192:195], v[26:29]
	v_mfma_f32_16x16x32_bf16 v[14:17], v[168:171], v[200:203], v[14:17]
	v_mfma_f32_16x16x32_bf16 v[10:13], v[176:179], v[200:203], v[10:13]
	v_mfma_f32_16x16x32_bf16 v[6:9], v[168:171], v[208:211], v[6:9]
	v_mfma_f32_16x16x32_bf16 v[2:5], v[176:179], v[208:211], v[2:5]
	v_mfma_f32_16x16x32_bf16 v[46:49], v[172:175], v[188:191], v[46:49]
	v_mfma_f32_16x16x32_bf16 v[42:45], v[180:183], v[188:191], v[42:45]
	v_mfma_f32_16x16x32_bf16 v[30:33], v[172:175], v[196:199], v[30:33]
	v_mfma_f32_16x16x32_bf16 v[26:29], v[180:183], v[196:199], v[26:29]
	v_mfma_f32_16x16x32_bf16 v[14:17], v[172:175], v[204:207], v[14:17]
	v_mfma_f32_16x16x32_bf16 v[10:13], v[180:183], v[204:207], v[10:13]
	v_mfma_f32_16x16x32_bf16 v[6:9], v[172:175], v[212:215], v[6:9]
	v_mfma_f32_16x16x32_bf16 v[2:5], v[180:183], v[212:215], v[2:5]
	s_barrier
	s_add_i32 s45, 0, 0x18000
	s_add_i32 s91, 0, 0x1c000
	v_add_u32_e32 v164, s45, v147
	v_add_u32_e32 v180, s91, v147
	ds_read_b128 v[152:155], v164
	ds_read_b128 v[156:159], v164 offset:1024
	ds_read_b128 v[160:163], v164 offset:2048
	ds_read_b128 v[164:167], v164 offset:3072
	ds_read_b128 v[168:171], v180
	ds_read_b128 v[172:175], v180 offset:1024
	ds_read_b128 v[176:179], v180 offset:2048
	ds_read_b128 v[180:183], v180 offset:3072
	s_add_u32 s56, s56, 0x40000
	s_addc_u32 s57, s57, 0
	s_mov_b32 m0, s63
	v_lshl_add_u64 v[224:225], s[56:57], 0, v[130:131]
	ds_read_b128 v[184:187], v151 offset:32768
	ds_read_b128 v[188:191], v151 offset:33792
	ds_read_b128 v[192:195], v151 offset:34816
	ds_read_b128 v[196:199], v151 offset:35840
	ds_read_b128 v[200:203], v151 offset:36864
	ds_read_b128 v[204:207], v151 offset:37888
	ds_read_b128 v[208:211], v151 offset:38912
	ds_read_b128 v[212:215], v151 offset:39936
	global_load_lds_dwordx4 v[224:225], off
	v_lshl_add_u64 v[224:225], s[56:57], 0, v[134:135]
	s_mov_b32 m0, s74
	s_nop 0
	global_load_lds_dwordx4 v[224:225], off
	s_waitcnt vmcnt(8)
	s_waitcnt lgkmcnt(0)
	s_barrier
	s_waitcnt lgkmcnt(0)
	v_mfma_f32_16x16x32_bf16 v[126:129], v[152:155], v[184:187], v[126:129]
	v_mfma_f32_16x16x32_bf16 v[122:125], v[160:163], v[184:187], v[122:125]
	v_mfma_f32_16x16x32_bf16 v[118:121], v[152:155], v[192:195], v[118:121]
	v_mfma_f32_16x16x32_bf16 v[114:117], v[160:163], v[192:195], v[114:117]
	v_mfma_f32_16x16x32_bf16 v[102:105], v[152:155], v[200:203], v[102:105]
	v_mfma_f32_16x16x32_bf16 v[98:101], v[160:163], v[200:203], v[98:101]
	v_mfma_f32_16x16x32_bf16 v[86:89], v[152:155], v[208:211], v[86:89]
	v_mfma_f32_16x16x32_bf16 v[82:85], v[160:163], v[208:211], v[82:85]
	v_mfma_f32_16x16x32_bf16 v[126:129], v[156:159], v[188:191], v[126:129]
	v_mfma_f32_16x16x32_bf16 v[122:125], v[164:167], v[188:191], v[122:125]
	v_mfma_f32_16x16x32_bf16 v[118:121], v[156:159], v[196:199], v[118:121]
	v_mfma_f32_16x16x32_bf16 v[114:117], v[164:167], v[196:199], v[114:117]
	v_mfma_f32_16x16x32_bf16 v[102:105], v[156:159], v[204:207], v[102:105]
	v_mfma_f32_16x16x32_bf16 v[98:101], v[164:167], v[204:207], v[98:101]
	v_mfma_f32_16x16x32_bf16 v[86:89], v[156:159], v[212:215], v[86:89]
	v_mfma_f32_16x16x32_bf16 v[82:85], v[164:167], v[212:215], v[82:85]
	v_mfma_f32_16x16x32_bf16 v[110:113], v[168:171], v[184:187], v[110:113]
	v_mfma_f32_16x16x32_bf16 v[106:109], v[176:179], v[184:187], v[106:109]
	v_mfma_f32_16x16x32_bf16 v[94:97], v[168:171], v[192:195], v[94:97]
	v_mfma_f32_16x16x32_bf16 v[90:93], v[176:179], v[192:195], v[90:93]
	v_mfma_f32_16x16x32_bf16 v[78:81], v[168:171], v[200:203], v[78:81]
	v_mfma_f32_16x16x32_bf16 v[74:77], v[176:179], v[200:203], v[74:77]
	v_mfma_f32_16x16x32_bf16 v[70:73], v[168:171], v[208:211], v[70:73]
	v_mfma_f32_16x16x32_bf16 v[66:69], v[176:179], v[208:211], v[66:69]
	v_mfma_f32_16x16x32_bf16 v[110:113], v[172:175], v[188:191], v[110:113]
	v_mfma_f32_16x16x32_bf16 v[106:109], v[180:183], v[188:191], v[106:109]
	v_mfma_f32_16x16x32_bf16 v[94:97], v[172:175], v[196:199], v[94:97]
	v_mfma_f32_16x16x32_bf16 v[90:93], v[180:183], v[196:199], v[90:93]
	v_mfma_f32_16x16x32_bf16 v[78:81], v[172:175], v[204:207], v[78:81]
	v_mfma_f32_16x16x32_bf16 v[74:77], v[180:183], v[204:207], v[74:77]
	v_mfma_f32_16x16x32_bf16 v[70:73], v[172:175], v[212:215], v[70:73]
	v_mfma_f32_16x16x32_bf16 v[66:69], v[180:183], v[212:215], v[66:69]
	s_barrier
	s_add_i32 s45, s45, s59
	v_lshl_add_u64 v[216:217], v[216:217], 0, s[14:15]
	s_mov_b32 m0, s45
	ds_read_b128 v[184:187], v151 offset:49152
	ds_read_b128 v[188:191], v151 offset:50176
	ds_read_b128 v[192:195], v151 offset:51200
	ds_read_b128 v[196:199], v151 offset:52224
	ds_read_b128 v[200:203], v151 offset:53248
	ds_read_b128 v[204:207], v151 offset:54272
	ds_read_b128 v[208:211], v151 offset:55296
	ds_read_b128 v[212:215], v151 offset:56320
	global_load_lds_dwordx4 v[216:217], off
	s_add_i32 m0, s45, 0x2000
	s_add_u32 s48, s48, 0x40080
	v_lshl_add_u64 v[216:217], v[218:219], 0, s[14:15]
	s_addc_u32 s49, s49, 0
	s_add_i32 s45, s91, s59
	global_load_lds_dwordx4 v[216:217], off
	v_lshl_add_u64 v[216:217], s[48:49], 0, v[132:133]
	s_mov_b32 m0, s45
	s_nop 0
	global_load_lds_dwordx4 v[216:217], off
	v_lshl_add_u64 v[216:217], s[48:49], 0, v[136:137]
	s_add_i32 m0, s45, 0x2000
	s_nop 0
	global_load_lds_dwordx4 v[216:217], off
	v_lshl_add_u64 v[216:217], v[220:221], 0, s[14:15]
	s_mov_b32 m0, s77
	s_nop 0
	global_load_lds_dwordx4 v[216:217], off
	v_lshl_add_u64 v[216:217], v[222:223], 0, s[14:15]
	s_mov_b32 m0, s78
	s_nop 0
	global_load_lds_dwordx4 v[216:217], off
	s_waitcnt vmcnt(8)
	s_waitcnt lgkmcnt(0)
	s_barrier
	s_waitcnt lgkmcnt(0)
	v_mfma_f32_16x16x32_bf16 v[62:65], v[152:155], v[184:187], v[62:65]
	v_mfma_f32_16x16x32_bf16 v[58:61], v[160:163], v[184:187], v[58:61]
	v_mfma_f32_16x16x32_bf16 v[54:57], v[152:155], v[192:195], v[54:57]
	v_mfma_f32_16x16x32_bf16 v[50:53], v[160:163], v[192:195], v[50:53]
	v_mfma_f32_16x16x32_bf16 v[38:41], v[152:155], v[200:203], v[38:41]
	v_mfma_f32_16x16x32_bf16 v[34:37], v[160:163], v[200:203], v[34:37]
	v_mfma_f32_16x16x32_bf16 v[22:25], v[152:155], v[208:211], v[22:25]
	v_mfma_f32_16x16x32_bf16 v[18:21], v[160:163], v[208:211], v[18:21]
	v_mfma_f32_16x16x32_bf16 v[62:65], v[156:159], v[188:191], v[62:65]
	v_mfma_f32_16x16x32_bf16 v[58:61], v[164:167], v[188:191], v[58:61]
	v_mfma_f32_16x16x32_bf16 v[54:57], v[156:159], v[196:199], v[54:57]
	v_mfma_f32_16x16x32_bf16 v[50:53], v[164:167], v[196:199], v[50:53]
	v_mfma_f32_16x16x32_bf16 v[38:41], v[156:159], v[204:207], v[38:41]
	v_mfma_f32_16x16x32_bf16 v[34:37], v[164:167], v[204:207], v[34:37]
	v_mfma_f32_16x16x32_bf16 v[22:25], v[156:159], v[212:215], v[22:25]
	v_mfma_f32_16x16x32_bf16 v[18:21], v[164:167], v[212:215], v[18:21]
	v_mfma_f32_16x16x32_bf16 v[46:49], v[168:171], v[184:187], v[46:49]
	v_mfma_f32_16x16x32_bf16 v[42:45], v[176:179], v[184:187], v[42:45]
	v_mfma_f32_16x16x32_bf16 v[30:33], v[168:171], v[192:195], v[30:33]
	v_mfma_f32_16x16x32_bf16 v[26:29], v[176:179], v[192:195], v[26:29]
	v_mfma_f32_16x16x32_bf16 v[14:17], v[168:171], v[200:203], v[14:17]
	v_mfma_f32_16x16x32_bf16 v[10:13], v[176:179], v[200:203], v[10:13]
	v_mfma_f32_16x16x32_bf16 v[6:9], v[168:171], v[208:211], v[6:9]
	v_mfma_f32_16x16x32_bf16 v[2:5], v[176:179], v[208:211], v[2:5]
	v_mfma_f32_16x16x32_bf16 v[46:49], v[172:175], v[188:191], v[46:49]
	v_mfma_f32_16x16x32_bf16 v[42:45], v[180:183], v[188:191], v[42:45]
	v_mfma_f32_16x16x32_bf16 v[30:33], v[172:175], v[196:199], v[30:33]
	v_mfma_f32_16x16x32_bf16 v[26:29], v[180:183], v[196:199], v[26:29]
	v_mfma_f32_16x16x32_bf16 v[14:17], v[172:175], v[204:207], v[14:17]
	v_mfma_f32_16x16x32_bf16 v[10:13], v[180:183], v[204:207], v[10:13]
	v_mfma_f32_16x16x32_bf16 v[6:9], v[172:175], v[212:215], v[6:9]
	v_mfma_f32_16x16x32_bf16 v[2:5], v[180:183], v[212:215], v[2:5]
	s_barrier
	s_add_i32 s44, s44, 2
	s_add_u32 s42, s42, 0x100
	s_addc_u32 s43, s43, 0
	s_add_u32 s27, s27, 0x100
	s_addc_u32 s31, s31, 0
	s_cmp_gt_u32 s44, 13
	s_cbranch_scc0 .LBB0_218
	s_setprio 0
	s_and_b64 vcc, exec, s[16:17]
	s_cbranch_vccz .LBB0_221
	s_barrier

.LBB0_589:
	s_add_u32 s10, s10, 0x40080
	s_addc_u32 s11, s11, 0
	s_add_u32 s16, s12, 0x100
	v_mov_b32_e32 v2, 0
	s_addc_u32 s44, s13, 0
	s_mov_b32 s45, -2
	v_mov_b32_e32 v3, v2
	v_mov_b32_e32 v4, v2
	v_mov_b32_e32 v5, v2
	v_mov_b32_e32 v6, v2
	v_mov_b32_e32 v7, v2
	v_mov_b32_e32 v8, v2
	v_mov_b32_e32 v9, v2
	v_mov_b32_e32 v10, v2
	v_mov_b32_e32 v11, v2
	v_mov_b32_e32 v12, v2
	v_mov_b32_e32 v13, v2
	v_mov_b32_e32 v14, v2
	v_mov_b32_e32 v15, v2
	v_mov_b32_e32 v16, v2
	v_mov_b32_e32 v17, v2
	v_mov_b32_e32 v18, v2
	v_mov_b32_e32 v19, v2
	v_mov_b32_e32 v20, v2
	v_mov_b32_e32 v21, v2
	v_mov_b32_e32 v22, v2
	v_mov_b32_e32 v23, v2
	v_mov_b32_e32 v24, v2
	v_mov_b32_e32 v25, v2
	v_mov_b32_e32 v26, v2
	v_mov_b32_e32 v27, v2
	v_mov_b32_e32 v28, v2
	v_mov_b32_e32 v29, v2
	v_mov_b32_e32 v30, v2
	v_mov_b32_e32 v31, v2
	v_mov_b32_e32 v32, v2
	v_mov_b32_e32 v33, v2
	v_mov_b32_e32 v66, v2
	v_mov_b32_e32 v67, v2
	v_mov_b32_e32 v68, v2
	v_mov_b32_e32 v69, v2
	v_mov_b32_e32 v70, v2
	v_mov_b32_e32 v71, v2
	v_mov_b32_e32 v72, v2
	v_mov_b32_e32 v73, v2
	v_mov_b32_e32 v74, v2
	v_mov_b32_e32 v75, v2
	v_mov_b32_e32 v76, v2
	v_mov_b32_e32 v77, v2
	v_mov_b32_e32 v78, v2
	v_mov_b32_e32 v79, v2
	v_mov_b32_e32 v80, v2
	v_mov_b32_e32 v81, v2
	v_mov_b32_e32 v82, v2
	v_mov_b32_e32 v83, v2
	v_mov_b32_e32 v84, v2
	v_mov_b32_e32 v85, v2
	v_mov_b32_e32 v86, v2
	v_mov_b32_e32 v87, v2
	v_mov_b32_e32 v88, v2
	v_mov_b32_e32 v89, v2
	v_mov_b32_e32 v90, v2
	v_mov_b32_e32 v91, v2
	v_mov_b32_e32 v92, v2
	v_mov_b32_e32 v93, v2
	v_mov_b32_e32 v94, v2
	v_mov_b32_e32 v95, v2
	v_mov_b32_e32 v96, v2
	v_mov_b32_e32 v97, v2
	v_mov_b32_e32 v34, v2
	v_mov_b32_e32 v35, v2
	v_mov_b32_e32 v36, v2
	v_mov_b32_e32 v37, v2
	v_mov_b32_e32 v38, v2
	v_mov_b32_e32 v39, v2
	v_mov_b32_e32 v40, v2
	v_mov_b32_e32 v41, v2
	v_mov_b32_e32 v42, v2
	v_mov_b32_e32 v43, v2
	v_mov_b32_e32 v44, v2
	v_mov_b32_e32 v45, v2
	v_mov_b32_e32 v46, v2
	v_mov_b32_e32 v47, v2
	v_mov_b32_e32 v48, v2
	v_mov_b32_e32 v49, v2
	v_mov_b32_e32 v50, v2
	v_mov_b32_e32 v51, v2
	v_mov_b32_e32 v52, v2
	v_mov_b32_e32 v53, v2
	v_mov_b32_e32 v54, v2
	v_mov_b32_e32 v55, v2
	v_mov_b32_e32 v56, v2
	v_mov_b32_e32 v57, v2
	v_mov_b32_e32 v58, v2
	v_mov_b32_e32 v59, v2
	v_mov_b32_e32 v60, v2
	v_mov_b32_e32 v61, v2
	v_mov_b32_e32 v62, v2
	v_mov_b32_e32 v63, v2
	v_mov_b32_e32 v64, v2
	v_mov_b32_e32 v65, v2
	v_mov_b32_e32 v98, v2
	v_mov_b32_e32 v99, v2
	v_mov_b32_e32 v100, v2
	v_mov_b32_e32 v101, v2
	v_mov_b32_e32 v102, v2
	v_mov_b32_e32 v103, v2
	v_mov_b32_e32 v104, v2
	v_mov_b32_e32 v105, v2
	v_mov_b32_e32 v106, v2
	v_mov_b32_e32 v107, v2
	v_mov_b32_e32 v108, v2
	v_mov_b32_e32 v109, v2
	v_mov_b32_e32 v110, v2
	v_mov_b32_e32 v111, v2
	v_mov_b32_e32 v112, v2
	v_mov_b32_e32 v113, v2
	v_mov_b32_e32 v114, v2
	v_mov_b32_e32 v115, v2
	v_mov_b32_e32 v116, v2
	v_mov_b32_e32 v117, v2
	v_mov_b32_e32 v118, v2
	v_mov_b32_e32 v119, v2
	v_mov_b32_e32 v120, v2
	v_mov_b32_e32 v121, v2
	v_mov_b32_e32 v122, v2
	v_mov_b32_e32 v123, v2
	v_mov_b32_e32 v124, v2
	v_mov_b32_e32 v125, v2
	v_mov_b32_e32 v126, v2
	v_mov_b32_e32 v127, v2
	v_mov_b32_e32 v128, v2
	v_mov_b32_e32 v129, v2
	v_cmp_gt_u32_e32 vcc, 0x100, v1
	s_cbranch_vccz .Lkprio_2
	s_setprio 1
.Lkprio_2:
.LBB0_590:
	ds_read_b128 v[130:133], v175
	ds_read_b128 v[134:137], v175 offset:1024
	ds_read_b128 v[156:159], v175 offset:2048
	ds_read_b128 v[160:163], v175 offset:3072
	ds_read_b128 v[164:167], v176
	ds_read_b128 v[168:171], v176 offset:1024
	ds_read_b128 v[180:183], v176 offset:2048
	ds_read_b128 v[184:187], v176 offset:3072
	s_add_u32 s12, s10, 0xfffc0080
	s_addc_u32 s13, s11, -1
	s_cmp_eq_u32 s45, 12
	s_cselect_b32 s63, s7, s13
	s_cselect_b32 s62, s6, s12
	s_cselect_b32 s13, s9, s44
	s_cselect_b32 s12, s8, s16
	v_lshl_add_u64 v[220:221], s[10:11], 0, v[148:149]
	s_add_i32 m0, s78, 0xc000
	ds_read_b128 v[188:191], v177
	ds_read_b128 v[192:195], v177 offset:1024
	ds_read_b128 v[196:199], v177 offset:2048
	ds_read_b128 v[200:203], v177 offset:3072
	ds_read_b128 v[204:207], v177 offset:4096
	ds_read_b128 v[208:211], v177 offset:5120
	ds_read_b128 v[212:215], v177 offset:6144
	ds_read_b128 v[216:219], v177 offset:7168
	global_load_lds_dwordx4 v[220:221], off
	v_lshl_add_u64 v[220:221], s[10:11], 0, v[150:151]
	s_add_i32 m0, s78, 0xe000
	s_nop 0
	global_load_lds_dwordx4 v[220:221], off
	s_waitcnt vmcnt(8)
	s_waitcnt lgkmcnt(0)
	s_barrier
	s_waitcnt lgkmcnt(0)
	v_mfma_f32_16x16x32_bf16 v[126:129], v[130:133], v[188:191], v[126:129]
	v_mfma_f32_16x16x32_bf16 v[122:125], v[156:159], v[188:191], v[122:125]
	v_mfma_f32_16x16x32_bf16 v[118:121], v[130:133], v[196:199], v[118:121]
	v_mfma_f32_16x16x32_bf16 v[114:117], v[156:159], v[196:199], v[114:117]
	v_mfma_f32_16x16x32_bf16 v[110:113], v[130:133], v[204:207], v[110:113]
	v_mfma_f32_16x16x32_bf16 v[106:109], v[156:159], v[204:207], v[106:109]
	v_mfma_f32_16x16x32_bf16 v[102:105], v[130:133], v[212:215], v[102:105]
	v_mfma_f32_16x16x32_bf16 v[98:101], v[156:159], v[212:215], v[98:101]
	v_mfma_f32_16x16x32_bf16 v[126:129], v[134:137], v[192:195], v[126:129]
	v_mfma_f32_16x16x32_bf16 v[122:125], v[160:163], v[192:195], v[122:125]
	v_mfma_f32_16x16x32_bf16 v[118:121], v[134:137], v[200:203], v[118:121]
	v_mfma_f32_16x16x32_bf16 v[114:117], v[160:163], v[200:203], v[114:117]
	v_mfma_f32_16x16x32_bf16 v[110:113], v[134:137], v[208:211], v[110:113]
	v_mfma_f32_16x16x32_bf16 v[106:109], v[160:163], v[208:211], v[106:109]
	v_mfma_f32_16x16x32_bf16 v[102:105], v[134:137], v[216:219], v[102:105]
	v_mfma_f32_16x16x32_bf16 v[98:101], v[160:163], v[216:219], v[98:101]
	v_mfma_f32_16x16x32_bf16 v[62:65], v[164:167], v[188:191], v[62:65]
	v_mfma_f32_16x16x32_bf16 v[58:61], v[180:183], v[188:191], v[58:61]
	v_mfma_f32_16x16x32_bf16 v[54:57], v[164:167], v[196:199], v[54:57]
	v_mfma_f32_16x16x32_bf16 v[50:53], v[180:183], v[196:199], v[50:53]
	v_mfma_f32_16x16x32_bf16 v[46:49], v[164:167], v[204:207], v[46:49]
	v_mfma_f32_16x16x32_bf16 v[42:45], v[180:183], v[204:207], v[42:45]
	v_mfma_f32_16x16x32_bf16 v[38:41], v[164:167], v[212:215], v[38:41]
	v_mfma_f32_16x16x32_bf16 v[34:37], v[180:183], v[212:215], v[34:37]
	v_mfma_f32_16x16x32_bf16 v[62:65], v[168:171], v[192:195], v[62:65]
	v_mfma_f32_16x16x32_bf16 v[58:61], v[184:187], v[192:195], v[58:61]
	v_mfma_f32_16x16x32_bf16 v[54:57], v[168:171], v[200:203], v[54:57]
	v_mfma_f32_16x16x32_bf16 v[50:53], v[184:187], v[200:203], v[50:53]
	v_mfma_f32_16x16x32_bf16 v[46:49], v[168:171], v[208:211], v[46:49]
	v_mfma_f32_16x16x32_bf16 v[42:45], v[184:187], v[208:211], v[42:45]
	v_mfma_f32_16x16x32_bf16 v[38:41], v[168:171], v[216:219], v[38:41]
	v_mfma_f32_16x16x32_bf16 v[34:37], v[184:187], v[216:219], v[34:37]
	s_barrier
	s_add_i32 s46, s87, s61
	v_lshl_add_u64 v[220:221], s[12:13], 0, v[140:141]
	s_mov_b32 m0, s46
	ds_read_b128 v[188:191], v177 offset:16384
	ds_read_b128 v[192:195], v177 offset:17408
	ds_read_b128 v[196:199], v177 offset:18432
	ds_read_b128 v[200:203], v177 offset:19456
	ds_read_b128 v[204:207], v177 offset:20480
	ds_read_b128 v[208:211], v177 offset:21504
	ds_read_b128 v[212:215], v177 offset:22528
	ds_read_b128 v[216:219], v177 offset:23552
	global_load_lds_dwordx4 v[220:221], off
	s_add_i32 m0, s46, 0x2000
	s_add_u32 s46, s12, 0x40000
	v_lshl_add_u64 v[222:223], s[12:13], 0, v[144:145]
	s_addc_u32 s47, s13, 0
	s_add_i32 s55, s88, s61
	global_load_lds_dwordx4 v[222:223], off
	v_lshl_add_u64 v[224:225], s[46:47], 0, v[140:141]
	s_mov_b32 m0, s55
	v_lshl_add_u64 v[226:227], s[62:63], 0, v[142:143]
	global_load_lds_dwordx4 v[224:225], off
	v_lshl_add_u64 v[224:225], s[46:47], 0, v[144:145]
	s_add_i32 m0, s55, 0x2000
	s_nop 0
	global_load_lds_dwordx4 v[224:225], off
	v_lshl_add_u64 v[224:225], s[62:63], 0, v[138:139]
	s_mov_b32 m0, s78
	s_nop 0
	global_load_lds_dwordx4 v[224:225], off
	s_mov_b32 m0, s79
	s_nop 0
	global_load_lds_dwordx4 v[226:227], off
	s_waitcnt vmcnt(8)
	s_waitcnt lgkmcnt(0)
	s_barrier
	s_waitcnt lgkmcnt(0)
	v_mfma_f32_16x16x32_bf16 v[94:97], v[130:133], v[188:191], v[94:97]
	v_mfma_f32_16x16x32_bf16 v[90:93], v[156:159], v[188:191], v[90:93]
	v_mfma_f32_16x16x32_bf16 v[86:89], v[130:133], v[196:199], v[86:89]
	v_mfma_f32_16x16x32_bf16 v[82:85], v[156:159], v[196:199], v[82:85]
	v_mfma_f32_16x16x32_bf16 v[78:81], v[130:133], v[204:207], v[78:81]
	v_mfma_f32_16x16x32_bf16 v[74:77], v[156:159], v[204:207], v[74:77]
	v_mfma_f32_16x16x32_bf16 v[70:73], v[130:133], v[212:215], v[70:73]
	v_mfma_f32_16x16x32_bf16 v[66:69], v[156:159], v[212:215], v[66:69]
	v_mfma_f32_16x16x32_bf16 v[94:97], v[134:137], v[192:195], v[94:97]
	v_mfma_f32_16x16x32_bf16 v[90:93], v[160:163], v[192:195], v[90:93]
	v_mfma_f32_16x16x32_bf16 v[86:89], v[134:137], v[200:203], v[86:89]
	v_mfma_f32_16x16x32_bf16 v[82:85], v[160:163], v[200:203], v[82:85]
	v_mfma_f32_16x16x32_bf16 v[78:81], v[134:137], v[208:211], v[78:81]
	v_mfma_f32_16x16x32_bf16 v[74:77], v[160:163], v[208:211], v[74:77]
	v_mfma_f32_16x16x32_bf16 v[70:73], v[134:137], v[216:219], v[70:73]
	v_mfma_f32_16x16x32_bf16 v[66:69], v[160:163], v[216:219], v[66:69]
	v_mfma_f32_16x16x32_bf16 v[30:33], v[164:167], v[188:191], v[30:33]
	v_mfma_f32_16x16x32_bf16 v[26:29], v[180:183], v[188:191], v[26:29]
	v_mfma_f32_16x16x32_bf16 v[22:25], v[164:167], v[196:199], v[22:25]
	v_mfma_f32_16x16x32_bf16 v[18:21], v[180:183], v[196:199], v[18:21]
	v_mfma_f32_16x16x32_bf16 v[14:17], v[164:167], v[204:207], v[14:17]
	v_mfma_f32_16x16x32_bf16 v[10:13], v[180:183], v[204:207], v[10:13]
	v_mfma_f32_16x16x32_bf16 v[6:9], v[164:167], v[212:215], v[6:9]
	v_mfma_f32_16x16x32_bf16 v[2:5], v[180:183], v[212:215], v[2:5]
	v_mfma_f32_16x16x32_bf16 v[30:33], v[168:171], v[192:195], v[30:33]
	v_mfma_f32_16x16x32_bf16 v[26:29], v[184:187], v[192:195], v[26:29]
	v_mfma_f32_16x16x32_bf16 v[22:25], v[168:171], v[200:203], v[22:25]
	v_mfma_f32_16x16x32_bf16 v[18:21], v[184:187], v[200:203], v[18:21]
	v_mfma_f32_16x16x32_bf16 v[14:17], v[168:171], v[208:211], v[14:17]
	v_mfma_f32_16x16x32_bf16 v[10:13], v[184:187], v[208:211], v[10:13]
	v_mfma_f32_16x16x32_bf16 v[6:9], v[168:171], v[216:219], v[6:9]
	v_mfma_f32_16x16x32_bf16 v[2:5], v[184:187], v[216:219], v[2:5]
	s_barrier
	s_add_i32 s55, 0, 0x18000
	v_add_u32_e32 v146, s55, v173
	s_add_i32 s74, 0, 0x1c000
	ds_read_b128 v[130:133], v146
	ds_read_b128 v[134:137], v146 offset:1024
	ds_read_b128 v[156:159], v146 offset:2048
	ds_read_b128 v[160:163], v146 offset:3072
	v_add_u32_e32 v146, s74, v173
	ds_read_b128 v[164:167], v146
	ds_read_b128 v[168:171], v146 offset:1024
	ds_read_b128 v[180:183], v146 offset:2048
	ds_read_b128 v[184:187], v146 offset:3072
	s_add_u32 s46, s62, 0x40000
	s_addc_u32 s47, s63, 0
	s_mov_b32 m0, s80
	v_lshl_add_u64 v[228:229], s[46:47], 0, v[138:139]
	ds_read_b128 v[188:191], v177 offset:32768
	ds_read_b128 v[192:195], v177 offset:33792
	ds_read_b128 v[196:199], v177 offset:34816
	ds_read_b128 v[200:203], v177 offset:35840
	ds_read_b128 v[204:207], v177 offset:36864
	ds_read_b128 v[208:211], v177 offset:37888
	ds_read_b128 v[212:215], v177 offset:38912
	ds_read_b128 v[216:219], v177 offset:39936
	global_load_lds_dwordx4 v[228:229], off
	v_lshl_add_u64 v[228:229], s[46:47], 0, v[142:143]
	s_mov_b32 m0, s81
	s_nop 0
	global_load_lds_dwordx4 v[228:229], off
	s_waitcnt vmcnt(8)
	s_waitcnt lgkmcnt(0)
	s_barrier
	s_waitcnt lgkmcnt(0)
	v_mfma_f32_16x16x32_bf16 v[126:129], v[130:133], v[188:191], v[126:129]
	v_mfma_f32_16x16x32_bf16 v[122:125], v[156:159], v[188:191], v[122:125]
	v_mfma_f32_16x16x32_bf16 v[118:121], v[130:133], v[196:199], v[118:121]
	v_mfma_f32_16x16x32_bf16 v[114:117], v[156:159], v[196:199], v[114:117]
	v_mfma_f32_16x16x32_bf16 v[110:113], v[130:133], v[204:207], v[110:113]
	v_mfma_f32_16x16x32_bf16 v[106:109], v[156:159], v[204:207], v[106:109]
	v_mfma_f32_16x16x32_bf16 v[102:105], v[130:133], v[212:215], v[102:105]
	v_mfma_f32_16x16x32_bf16 v[98:101], v[156:159], v[212:215], v[98:101]
	v_mfma_f32_16x16x32_bf16 v[126:129], v[134:137], v[192:195], v[126:129]
	v_mfma_f32_16x16x32_bf16 v[122:125], v[160:163], v[192:195], v[122:125]
	v_mfma_f32_16x16x32_bf16 v[118:121], v[134:137], v[200:203], v[118:121]
	v_mfma_f32_16x16x32_bf16 v[114:117], v[160:163], v[200:203], v[114:117]
	v_mfma_f32_16x16x32_bf16 v[110:113], v[134:137], v[208:211], v[110:113]
	v_mfma_f32_16x16x32_bf16 v[106:109], v[160:163], v[208:211], v[106:109]
	v_mfma_f32_16x16x32_bf16 v[102:105], v[134:137], v[216:219], v[102:105]
	v_mfma_f32_16x16x32_bf16 v[98:101], v[160:163], v[216:219], v[98:101]
	v_mfma_f32_16x16x32_bf16 v[62:65], v[164:167], v[188:191], v[62:65]
	v_mfma_f32_16x16x32_bf16 v[58:61], v[180:183], v[188:191], v[58:61]
	v_mfma_f32_16x16x32_bf16 v[54:57], v[164:167], v[196:199], v[54:57]
	v_mfma_f32_16x16x32_bf16 v[50:53], v[180:183], v[196:199], v[50:53]
	v_mfma_f32_16x16x32_bf16 v[46:49], v[164:167], v[204:207], v[46:49]
	v_mfma_f32_16x16x32_bf16 v[42:45], v[180:183], v[204:207], v[42:45]
	v_mfma_f32_16x16x32_bf16 v[38:41], v[164:167], v[212:215], v[38:41]
	v_mfma_f32_16x16x32_bf16 v[34:37], v[180:183], v[212:215], v[34:37]
	v_mfma_f32_16x16x32_bf16 v[62:65], v[168:171], v[192:195], v[62:65]
	v_mfma_f32_16x16x32_bf16 v[58:61], v[184:187], v[192:195], v[58:61]
	v_mfma_f32_16x16x32_bf16 v[54:57], v[168:171], v[200:203], v[54:57]
	v_mfma_f32_16x16x32_bf16 v[50:53], v[184:187], v[200:203], v[50:53]
	v_mfma_f32_16x16x32_bf16 v[46:49], v[168:171], v[208:211], v[46:49]
	v_mfma_f32_16x16x32_bf16 v[42:45], v[184:187], v[208:211], v[42:45]
	v_mfma_f32_16x16x32_bf16 v[38:41], v[168:171], v[216:219], v[38:41]
	v_mfma_f32_16x16x32_bf16 v[34:37], v[184:187], v[216:219], v[34:37]
	s_barrier
	s_add_i32 s46, s55, s61
	v_lshl_add_u64 v[220:221], v[220:221], 0, s[38:39]
	s_mov_b32 m0, s46
	ds_read_b128 v[188:191], v177 offset:49152
	ds_read_b128 v[192:195], v177 offset:50176
	ds_read_b128 v[196:199], v177 offset:51200
	ds_read_b128 v[200:203], v177 offset:52224
	ds_read_b128 v[204:207], v177 offset:53248
	ds_read_b128 v[208:211], v177 offset:54272
	ds_read_b128 v[212:215], v177 offset:55296
	ds_read_b128 v[216:219], v177 offset:56320
	global_load_lds_dwordx4 v[220:221], off
	s_add_i32 m0, s46, 0x2000
	s_add_u32 s12, s12, 0x40080
	v_lshl_add_u64 v[220:221], v[222:223], 0, s[38:39]
	s_addc_u32 s13, s13, 0
	s_add_i32 s46, s74, s61
	global_load_lds_dwordx4 v[220:221], off
	v_lshl_add_u64 v[220:221], s[12:13], 0, v[140:141]
	s_mov_b32 m0, s46
	s_nop 0
	global_load_lds_dwordx4 v[220:221], off
	v_lshl_add_u64 v[220:221], s[12:13], 0, v[144:145]
	s_add_i32 m0, s46, 0x2000
	s_nop 0
	global_load_lds_dwordx4 v[220:221], off
	v_lshl_add_u64 v[220:221], v[224:225], 0, s[38:39]
	s_mov_b32 m0, s84
	s_nop 0
	global_load_lds_dwordx4 v[220:221], off
	v_lshl_add_u64 v[220:221], v[226:227], 0, s[38:39]
	s_mov_b32 m0, s85
	s_nop 0
	global_load_lds_dwordx4 v[220:221], off
	s_waitcnt vmcnt(8)
	s_waitcnt lgkmcnt(0)
	s_barrier
	s_waitcnt lgkmcnt(0)
	v_mfma_f32_16x16x32_bf16 v[94:97], v[130:133], v[188:191], v[94:97]
	v_mfma_f32_16x16x32_bf16 v[90:93], v[156:159], v[188:191], v[90:93]
	v_mfma_f32_16x16x32_bf16 v[86:89], v[130:133], v[196:199], v[86:89]
	v_mfma_f32_16x16x32_bf16 v[82:85], v[156:159], v[196:199], v[82:85]
	v_mfma_f32_16x16x32_bf16 v[78:81], v[130:133], v[204:207], v[78:81]
	v_mfma_f32_16x16x32_bf16 v[74:77], v[156:159], v[204:207], v[74:77]
	v_mfma_f32_16x16x32_bf16 v[70:73], v[130:133], v[212:215], v[70:73]
	v_mfma_f32_16x16x32_bf16 v[66:69], v[156:159], v[212:215], v[66:69]
	v_mfma_f32_16x16x32_bf16 v[94:97], v[134:137], v[192:195], v[94:97]
	v_mfma_f32_16x16x32_bf16 v[90:93], v[160:163], v[192:195], v[90:93]
	v_mfma_f32_16x16x32_bf16 v[86:89], v[134:137], v[200:203], v[86:89]
	v_mfma_f32_16x16x32_bf16 v[82:85], v[160:163], v[200:203], v[82:85]
	v_mfma_f32_16x16x32_bf16 v[78:81], v[134:137], v[208:211], v[78:81]
	v_mfma_f32_16x16x32_bf16 v[74:77], v[160:163], v[208:211], v[74:77]
	v_mfma_f32_16x16x32_bf16 v[70:73], v[134:137], v[216:219], v[70:73]
	v_mfma_f32_16x16x32_bf16 v[66:69], v[160:163], v[216:219], v[66:69]
	v_mfma_f32_16x16x32_bf16 v[30:33], v[164:167], v[188:191], v[30:33]
	v_mfma_f32_16x16x32_bf16 v[26:29], v[180:183], v[188:191], v[26:29]
	v_mfma_f32_16x16x32_bf16 v[22:25], v[164:167], v[196:199], v[22:25]
	v_mfma_f32_16x16x32_bf16 v[18:21], v[180:183], v[196:199], v[18:21]
	v_mfma_f32_16x16x32_bf16 v[14:17], v[164:167], v[204:207], v[14:17]
	v_mfma_f32_16x16x32_bf16 v[10:13], v[180:183], v[204:207], v[10:13]
	v_mfma_f32_16x16x32_bf16 v[6:9], v[164:167], v[212:215], v[6:9]
	v_mfma_f32_16x16x32_bf16 v[2:5], v[180:183], v[212:215], v[2:5]
	v_mfma_f32_16x16x32_bf16 v[30:33], v[168:171], v[192:195], v[30:33]
	v_mfma_f32_16x16x32_bf16 v[26:29], v[184:187], v[192:195], v[26:29]
	v_mfma_f32_16x16x32_bf16 v[22:25], v[168:171], v[200:203], v[22:25]
	v_mfma_f32_16x16x32_bf16 v[18:21], v[184:187], v[200:203], v[18:21]
	v_mfma_f32_16x16x32_bf16 v[14:17], v[168:171], v[208:211], v[14:17]
	v_mfma_f32_16x16x32_bf16 v[10:13], v[184:187], v[208:211], v[10:13]
	v_mfma_f32_16x16x32_bf16 v[6:9], v[168:171], v[216:219], v[6:9]
	v_mfma_f32_16x16x32_bf16 v[2:5], v[184:187], v[216:219], v[2:5]
	s_barrier
	s_add_i32 s45, s45, 2
	s_add_u32 s10, s10, 0x100
	s_addc_u32 s11, s11, 0
	s_add_u32 s16, s16, 0x100
	s_addc_u32 s44, s44, 0
	s_cmp_gt_u32 s45, 13
	s_cbranch_scc0 .LBB0_590
	s_setprio 0
	s_and_b64 vcc, exec, s[40:41]
	s_cbranch_vccz .LBB0_593
	s_barrier

.LBB0_1096:
	s_add_u32 s48, s48, 0x40080
	s_addc_u32 s49, s49, 0
	s_add_u32 s31, s50, 0x100
	s_addc_u32 s35, s51, 0
	s_mov_b32 s44, -2
	v_cmp_gt_u32_e32 vcc, 0x100, v1
	s_cbranch_vccz .Lkprio_3
	s_setprio 1
.Lkprio_3:
.LBB0_1097:
	v_add_u32_e32 v158, s79, v161
	ds_read_b128 v[146:149], v158
	ds_read_b128 v[150:153], v158 offset:1024
	ds_read_b128 v[154:157], v158 offset:2048
	ds_read_b128 v[164:167], v158 offset:3072
	v_add_u32_e32 v158, s80, v161
	ds_read_b128 v[168:171], v158
	ds_read_b128 v[172:175], v158 offset:1024
	ds_read_b128 v[176:179], v158 offset:2048
	ds_read_b128 v[180:183], v158 offset:3072
	s_add_u32 s45, s48, 0xfffc0080
	s_addc_u32 s47, s49, -1
	s_cmp_eq_u32 s44, 12
	s_cselect_b32 s53, s41, s47
	s_cselect_b32 s52, s40, s45
	s_cselect_b32 s51, s43, s35
	s_cselect_b32 s50, s42, s31
	v_lshl_add_u64 v[158:159], s[48:49], 0, v[138:139]
	s_add_i32 m0, s58, 0xc000
	ds_read_b128 v[184:187], v163
	ds_read_b128 v[188:191], v163 offset:1024
	ds_read_b128 v[192:195], v163 offset:2048
	ds_read_b128 v[196:199], v163 offset:3072
	ds_read_b128 v[200:203], v163 offset:4096
	ds_read_b128 v[204:207], v163 offset:5120
	ds_read_b128 v[208:211], v163 offset:6144
	ds_read_b128 v[212:215], v163 offset:7168
	global_load_lds_dwordx4 v[158:159], off
	v_lshl_add_u64 v[158:159], s[48:49], 0, v[140:141]
	s_add_i32 m0, s58, 0xe000
	s_nop 0
	global_load_lds_dwordx4 v[158:159], off
	s_waitcnt vmcnt(8)
	s_waitcnt lgkmcnt(0)
	s_barrier
	s_waitcnt lgkmcnt(0)
	v_mfma_f32_16x16x32_bf16 v[126:129], v[146:149], v[184:187], v[126:129]
	v_mfma_f32_16x16x32_bf16 v[122:125], v[154:157], v[184:187], v[122:125]
	v_mfma_f32_16x16x32_bf16 v[118:121], v[146:149], v[192:195], v[118:121]
	v_mfma_f32_16x16x32_bf16 v[114:117], v[154:157], v[192:195], v[114:117]
	v_mfma_f32_16x16x32_bf16 v[110:113], v[146:149], v[200:203], v[110:113]
	v_mfma_f32_16x16x32_bf16 v[106:109], v[154:157], v[200:203], v[106:109]
	v_mfma_f32_16x16x32_bf16 v[102:105], v[146:149], v[208:211], v[102:105]
	v_mfma_f32_16x16x32_bf16 v[98:101], v[154:157], v[208:211], v[98:101]
	v_mfma_f32_16x16x32_bf16 v[126:129], v[150:153], v[188:191], v[126:129]
	v_mfma_f32_16x16x32_bf16 v[122:125], v[164:167], v[188:191], v[122:125]
	v_mfma_f32_16x16x32_bf16 v[118:121], v[150:153], v[196:199], v[118:121]
	v_mfma_f32_16x16x32_bf16 v[114:117], v[164:167], v[196:199], v[114:117]
	v_mfma_f32_16x16x32_bf16 v[110:113], v[150:153], v[204:207], v[110:113]
	v_mfma_f32_16x16x32_bf16 v[106:109], v[164:167], v[204:207], v[106:109]
	v_mfma_f32_16x16x32_bf16 v[102:105], v[150:153], v[212:215], v[102:105]
	v_mfma_f32_16x16x32_bf16 v[98:101], v[164:167], v[212:215], v[98:101]
	v_mfma_f32_16x16x32_bf16 v[94:97], v[168:171], v[184:187], v[94:97]
	v_mfma_f32_16x16x32_bf16 v[90:93], v[176:179], v[184:187], v[90:93]
	v_mfma_f32_16x16x32_bf16 v[86:89], v[168:171], v[192:195], v[86:89]
	v_mfma_f32_16x16x32_bf16 v[82:85], v[176:179], v[192:195], v[82:85]
	v_mfma_f32_16x16x32_bf16 v[78:81], v[168:171], v[200:203], v[78:81]
	v_mfma_f32_16x16x32_bf16 v[74:77], v[176:179], v[200:203], v[74:77]
	v_mfma_f32_16x16x32_bf16 v[70:73], v[168:171], v[208:211], v[70:73]
	v_mfma_f32_16x16x32_bf16 v[66:69], v[176:179], v[208:211], v[66:69]
	v_mfma_f32_16x16x32_bf16 v[94:97], v[172:175], v[188:191], v[94:97]
	v_mfma_f32_16x16x32_bf16 v[90:93], v[180:183], v[188:191], v[90:93]
	v_mfma_f32_16x16x32_bf16 v[86:89], v[172:175], v[196:199], v[86:89]
	v_mfma_f32_16x16x32_bf16 v[82:85], v[180:183], v[196:199], v[82:85]
	v_mfma_f32_16x16x32_bf16 v[78:81], v[172:175], v[204:207], v[78:81]
	v_mfma_f32_16x16x32_bf16 v[74:77], v[180:183], v[204:207], v[74:77]
	v_mfma_f32_16x16x32_bf16 v[70:73], v[172:175], v[212:215], v[70:73]
	v_mfma_f32_16x16x32_bf16 v[66:69], v[180:183], v[212:215], v[66:69]
	s_barrier
	s_add_i32 s45, s79, s57
	v_lshl_add_u64 v[158:159], s[50:51], 0, v[132:133]
	s_mov_b32 m0, s45
	ds_read_b128 v[184:187], v163 offset:16384
	ds_read_b128 v[188:191], v163 offset:17408
	ds_read_b128 v[192:195], v163 offset:18432
	ds_read_b128 v[196:199], v163 offset:19456
	ds_read_b128 v[200:203], v163 offset:20480
	ds_read_b128 v[204:207], v163 offset:21504
	ds_read_b128 v[208:211], v163 offset:22528
	ds_read_b128 v[212:215], v163 offset:23552
	global_load_lds_dwordx4 v[158:159], off
	s_add_i32 m0, s45, 0x2000
	s_add_u32 s84, s50, 0x40000
	v_lshl_add_u64 v[216:217], s[50:51], 0, v[136:137]
	s_addc_u32 s85, s51, 0
	s_add_i32 s45, s80, s57
	global_load_lds_dwordx4 v[216:217], off
	v_lshl_add_u64 v[218:219], s[84:85], 0, v[132:133]
	s_mov_b32 m0, s45
	v_lshl_add_u64 v[220:221], s[52:53], 0, v[134:135]
	global_load_lds_dwordx4 v[218:219], off
	v_lshl_add_u64 v[218:219], s[84:85], 0, v[136:137]
	s_add_i32 m0, s45, 0x2000
	s_nop 0
	global_load_lds_dwordx4 v[218:219], off
	v_lshl_add_u64 v[218:219], s[52:53], 0, v[130:131]
	s_mov_b32 m0, s58
	s_nop 0
	global_load_lds_dwordx4 v[218:219], off
	s_mov_b32 m0, s59
	s_nop 0
	global_load_lds_dwordx4 v[220:221], off
	s_waitcnt vmcnt(8)
	s_waitcnt lgkmcnt(0)
	s_barrier
	s_waitcnt lgkmcnt(0)
	v_mfma_f32_16x16x32_bf16 v[62:65], v[146:149], v[184:187], v[62:65]
	v_mfma_f32_16x16x32_bf16 v[58:61], v[154:157], v[184:187], v[58:61]
	v_mfma_f32_16x16x32_bf16 v[54:57], v[146:149], v[192:195], v[54:57]
	v_mfma_f32_16x16x32_bf16 v[50:53], v[154:157], v[192:195], v[50:53]
	v_mfma_f32_16x16x32_bf16 v[46:49], v[146:149], v[200:203], v[46:49]
	v_mfma_f32_16x16x32_bf16 v[42:45], v[154:157], v[200:203], v[42:45]
	v_mfma_f32_16x16x32_bf16 v[38:41], v[146:149], v[208:211], v[38:41]
	v_mfma_f32_16x16x32_bf16 v[34:37], v[154:157], v[208:211], v[34:37]
	v_mfma_f32_16x16x32_bf16 v[62:65], v[150:153], v[188:191], v[62:65]
	v_mfma_f32_16x16x32_bf16 v[58:61], v[164:167], v[188:191], v[58:61]
	v_mfma_f32_16x16x32_bf16 v[54:57], v[150:153], v[196:199], v[54:57]
	v_mfma_f32_16x16x32_bf16 v[50:53], v[164:167], v[196:199], v[50:53]
	v_mfma_f32_16x16x32_bf16 v[46:49], v[150:153], v[204:207], v[46:49]
	v_mfma_f32_16x16x32_bf16 v[42:45], v[164:167], v[204:207], v[42:45]
	v_mfma_f32_16x16x32_bf16 v[38:41], v[150:153], v[212:215], v[38:41]
	v_mfma_f32_16x16x32_bf16 v[34:37], v[164:167], v[212:215], v[34:37]
	v_mfma_f32_16x16x32_bf16 v[30:33], v[168:171], v[184:187], v[30:33]
	v_mfma_f32_16x16x32_bf16 v[26:29], v[176:179], v[184:187], v[26:29]
	v_mfma_f32_16x16x32_bf16 v[22:25], v[168:171], v[192:195], v[22:25]
	v_mfma_f32_16x16x32_bf16 v[18:21], v[176:179], v[192:195], v[18:21]
	v_mfma_f32_16x16x32_bf16 v[14:17], v[168:171], v[200:203], v[14:17]
	v_mfma_f32_16x16x32_bf16 v[10:13], v[176:179], v[200:203], v[10:13]
	v_mfma_f32_16x16x32_bf16 v[6:9], v[168:171], v[208:211], v[6:9]
	v_mfma_f32_16x16x32_bf16 v[2:5], v[176:179], v[208:211], v[2:5]
	v_mfma_f32_16x16x32_bf16 v[30:33], v[172:175], v[188:191], v[30:33]
	v_mfma_f32_16x16x32_bf16 v[26:29], v[180:183], v[188:191], v[26:29]
	v_mfma_f32_16x16x32_bf16 v[22:25], v[172:175], v[196:199], v[22:25]
	v_mfma_f32_16x16x32_bf16 v[18:21], v[180:183], v[196:199], v[18:21]
	v_mfma_f32_16x16x32_bf16 v[14:17], v[172:175], v[204:207], v[14:17]
	v_mfma_f32_16x16x32_bf16 v[10:13], v[180:183], v[204:207], v[10:13]
	v_mfma_f32_16x16x32_bf16 v[6:9], v[172:175], v[212:215], v[6:9]
	v_mfma_f32_16x16x32_bf16 v[2:5], v[180:183], v[212:215], v[2:5]
	s_barrier
	s_add_i32 s45, 0, 0x18000
	s_add_i32 s47, 0, 0x1c000
	v_add_u32_e32 v164, s45, v161
	v_add_u32_e32 v180, s47, v161
	ds_read_b128 v[146:149], v164
	ds_read_b128 v[150:153], v164 offset:1024
	ds_read_b128 v[154:157], v164 offset:2048
	ds_read_b128 v[164:167], v164 offset:3072
	ds_read_b128 v[168:171], v180
	ds_read_b128 v[172:175], v180 offset:1024
	ds_read_b128 v[176:179], v180 offset:2048
	ds_read_b128 v[180:183], v180 offset:3072
	s_add_u32 s52, s52, 0x40000
	s_addc_u32 s53, s53, 0
	s_mov_b32 m0, s60
	v_lshl_add_u64 v[222:223], s[52:53], 0, v[130:131]
	ds_read_b128 v[184:187], v163 offset:32768
	ds_read_b128 v[188:191], v163 offset:33792
	ds_read_b128 v[192:195], v163 offset:34816
	ds_read_b128 v[196:199], v163 offset:35840
	ds_read_b128 v[200:203], v163 offset:36864
	ds_read_b128 v[204:207], v163 offset:37888
	ds_read_b128 v[208:211], v163 offset:38912
	ds_read_b128 v[212:215], v163 offset:39936
	global_load_lds_dwordx4 v[222:223], off
	v_lshl_add_u64 v[222:223], s[52:53], 0, v[134:135]
	s_mov_b32 m0, s61
	s_nop 0
	global_load_lds_dwordx4 v[222:223], off
	s_waitcnt vmcnt(8)
	s_waitcnt lgkmcnt(0)
	s_barrier
	s_waitcnt lgkmcnt(0)
	v_mfma_f32_16x16x32_bf16 v[126:129], v[146:149], v[184:187], v[126:129]
	v_mfma_f32_16x16x32_bf16 v[122:125], v[154:157], v[184:187], v[122:125]
	v_mfma_f32_16x16x32_bf16 v[118:121], v[146:149], v[192:195], v[118:121]
	v_mfma_f32_16x16x32_bf16 v[114:117], v[154:157], v[192:195], v[114:117]
	v_mfma_f32_16x16x32_bf16 v[110:113], v[146:149], v[200:203], v[110:113]
	v_mfma_f32_16x16x32_bf16 v[106:109], v[154:157], v[200:203], v[106:109]
	v_mfma_f32_16x16x32_bf16 v[102:105], v[146:149], v[208:211], v[102:105]
	v_mfma_f32_16x16x32_bf16 v[98:101], v[154:157], v[208:211], v[98:101]
	v_mfma_f32_16x16x32_bf16 v[126:129], v[150:153], v[188:191], v[126:129]
	v_mfma_f32_16x16x32_bf16 v[122:125], v[164:167], v[188:191], v[122:125]
	v_mfma_f32_16x16x32_bf16 v[118:121], v[150:153], v[196:199], v[118:121]
	v_mfma_f32_16x16x32_bf16 v[114:117], v[164:167], v[196:199], v[114:117]
	v_mfma_f32_16x16x32_bf16 v[110:113], v[150:153], v[204:207], v[110:113]
	v_mfma_f32_16x16x32_bf16 v[106:109], v[164:167], v[204:207], v[106:109]
	v_mfma_f32_16x16x32_bf16 v[102:105], v[150:153], v[212:215], v[102:105]
	v_mfma_f32_16x16x32_bf16 v[98:101], v[164:167], v[212:215], v[98:101]
	v_mfma_f32_16x16x32_bf16 v[94:97], v[168:171], v[184:187], v[94:97]
	v_mfma_f32_16x16x32_bf16 v[90:93], v[176:179], v[184:187], v[90:93]
	v_mfma_f32_16x16x32_bf16 v[86:89], v[168:171], v[192:195], v[86:89]
	v_mfma_f32_16x16x32_bf16 v[82:85], v[176:179], v[192:195], v[82:85]
	v_mfma_f32_16x16x32_bf16 v[78:81], v[168:171], v[200:203], v[78:81]
	v_mfma_f32_16x16x32_bf16 v[74:77], v[176:179], v[200:203], v[74:77]
	v_mfma_f32_16x16x32_bf16 v[70:73], v[168:171], v[208:211], v[70:73]
	v_mfma_f32_16x16x32_bf16 v[66:69], v[176:179], v[208:211], v[66:69]
	v_mfma_f32_16x16x32_bf16 v[94:97], v[172:175], v[188:191], v[94:97]
	v_mfma_f32_16x16x32_bf16 v[90:93], v[180:183], v[188:191], v[90:93]
	v_mfma_f32_16x16x32_bf16 v[86:89], v[172:175], v[196:199], v[86:89]
	v_mfma_f32_16x16x32_bf16 v[82:85], v[180:183], v[196:199], v[82:85]
	v_mfma_f32_16x16x32_bf16 v[78:81], v[172:175], v[204:207], v[78:81]
	v_mfma_f32_16x16x32_bf16 v[74:77], v[180:183], v[204:207], v[74:77]
	v_mfma_f32_16x16x32_bf16 v[70:73], v[172:175], v[212:215], v[70:73]
	v_mfma_f32_16x16x32_bf16 v[66:69], v[180:183], v[212:215], v[66:69]
	s_barrier
	s_add_i32 s45, s45, s57
	v_lshl_add_u64 v[158:159], v[158:159], 0, s[18:19]
	s_mov_b32 m0, s45
	ds_read_b128 v[184:187], v163 offset:49152
	ds_read_b128 v[188:191], v163 offset:50176
	ds_read_b128 v[192:195], v163 offset:51200
	ds_read_b128 v[196:199], v163 offset:52224
	ds_read_b128 v[200:203], v163 offset:53248
	ds_read_b128 v[204:207], v163 offset:54272
	ds_read_b128 v[208:211], v163 offset:55296
	ds_read_b128 v[212:215], v163 offset:56320
	global_load_lds_dwordx4 v[158:159], off
	s_add_i32 m0, s45, 0x2000
	s_add_u32 s50, s50, 0x40080
	v_lshl_add_u64 v[158:159], v[216:217], 0, s[18:19]
	s_addc_u32 s51, s51, 0
	s_add_i32 s45, s47, s57
	global_load_lds_dwordx4 v[158:159], off
	v_lshl_add_u64 v[158:159], s[50:51], 0, v[132:133]
	s_mov_b32 m0, s45
	s_nop 0
	global_load_lds_dwordx4 v[158:159], off
	v_lshl_add_u64 v[158:159], s[50:51], 0, v[136:137]
	s_add_i32 m0, s45, 0x2000
	s_nop 0
	global_load_lds_dwordx4 v[158:159], off
	v_lshl_add_u64 v[158:159], v[218:219], 0, s[18:19]
	s_mov_b32 m0, s77
	s_nop 0
	global_load_lds_dwordx4 v[158:159], off
	v_lshl_add_u64 v[158:159], v[220:221], 0, s[18:19]
	s_mov_b32 m0, s78
	s_nop 0
	global_load_lds_dwordx4 v[158:159], off
	s_waitcnt vmcnt(8)
	s_waitcnt lgkmcnt(0)
	s_barrier
	s_waitcnt lgkmcnt(0)
	v_mfma_f32_16x16x32_bf16 v[62:65], v[146:149], v[184:187], v[62:65]
	v_mfma_f32_16x16x32_bf16 v[58:61], v[154:157], v[184:187], v[58:61]
	v_mfma_f32_16x16x32_bf16 v[54:57], v[146:149], v[192:195], v[54:57]
	v_mfma_f32_16x16x32_bf16 v[50:53], v[154:157], v[192:195], v[50:53]
	v_mfma_f32_16x16x32_bf16 v[46:49], v[146:149], v[200:203], v[46:49]
	v_mfma_f32_16x16x32_bf16 v[42:45], v[154:157], v[200:203], v[42:45]
	v_mfma_f32_16x16x32_bf16 v[38:41], v[146:149], v[208:211], v[38:41]
	v_mfma_f32_16x16x32_bf16 v[34:37], v[154:157], v[208:211], v[34:37]
	v_mfma_f32_16x16x32_bf16 v[62:65], v[150:153], v[188:191], v[62:65]
	v_mfma_f32_16x16x32_bf16 v[58:61], v[164:167], v[188:191], v[58:61]
	v_mfma_f32_16x16x32_bf16 v[54:57], v[150:153], v[196:199], v[54:57]
	v_mfma_f32_16x16x32_bf16 v[50:53], v[164:167], v[196:199], v[50:53]
	v_mfma_f32_16x16x32_bf16 v[46:49], v[150:153], v[204:207], v[46:49]
	v_mfma_f32_16x16x32_bf16 v[42:45], v[164:167], v[204:207], v[42:45]
	v_mfma_f32_16x16x32_bf16 v[38:41], v[150:153], v[212:215], v[38:41]
	v_mfma_f32_16x16x32_bf16 v[34:37], v[164:167], v[212:215], v[34:37]
	v_mfma_f32_16x16x32_bf16 v[30:33], v[168:171], v[184:187], v[30:33]
	v_mfma_f32_16x16x32_bf16 v[26:29], v[176:179], v[184:187], v[26:29]
	v_mfma_f32_16x16x32_bf16 v[22:25], v[168:171], v[192:195], v[22:25]
	v_mfma_f32_16x16x32_bf16 v[18:21], v[176:179], v[192:195], v[18:21]
	v_mfma_f32_16x16x32_bf16 v[14:17], v[168:171], v[200:203], v[14:17]
	v_mfma_f32_16x16x32_bf16 v[10:13], v[176:179], v[200:203], v[10:13]
	v_mfma_f32_16x16x32_bf16 v[6:9], v[168:171], v[208:211], v[6:9]
	v_mfma_f32_16x16x32_bf16 v[2:5], v[176:179], v[208:211], v[2:5]
	v_mfma_f32_16x16x32_bf16 v[30:33], v[172:175], v[188:191], v[30:33]
	v_mfma_f32_16x16x32_bf16 v[26:29], v[180:183], v[188:191], v[26:29]
	v_mfma_f32_16x16x32_bf16 v[22:25], v[172:175], v[196:199], v[22:25]
	v_mfma_f32_16x16x32_bf16 v[18:21], v[180:183], v[196:199], v[18:21]
	v_mfma_f32_16x16x32_bf16 v[14:17], v[172:175], v[204:207], v[14:17]
	v_mfma_f32_16x16x32_bf16 v[10:13], v[180:183], v[204:207], v[10:13]
	v_mfma_f32_16x16x32_bf16 v[6:9], v[172:175], v[212:215], v[6:9]
	v_mfma_f32_16x16x32_bf16 v[2:5], v[180:183], v[212:215], v[2:5]
	s_barrier
	s_add_i32 s44, s44, 2
	s_add_u32 s48, s48, 0x100
	s_addc_u32 s49, s49, 0
	s_add_u32 s31, s31, 0x100
	s_addc_u32 s35, s35, 0
	s_cmp_gt_u32 s44, 13
	s_cbranch_scc0 .LBB0_1097
	s_setprio 0
	s_and_b64 vcc, exec, s[20:21]
	s_cbranch_vccz .LBB0_1100
	s_barrier

.LBB0_1253:
	s_add_u32 s12, s12, 0x40080
	s_addc_u32 s13, s13, 0
	s_add_u32 s7, s14, 0x100
	v_mov_b32_e32 v2, 0
	s_addc_u32 s19, s15, 0
	s_mov_b32 s39, -2
	v_mov_b32_e32 v3, v2
	v_mov_b32_e32 v4, v2
	v_mov_b32_e32 v5, v2
	v_mov_b32_e32 v6, v2
	v_mov_b32_e32 v7, v2
	v_mov_b32_e32 v8, v2
	v_mov_b32_e32 v9, v2
	v_mov_b32_e32 v10, v2
	v_mov_b32_e32 v11, v2
	v_mov_b32_e32 v12, v2
	v_mov_b32_e32 v13, v2
	v_mov_b32_e32 v14, v2
	v_mov_b32_e32 v15, v2
	v_mov_b32_e32 v16, v2
	v_mov_b32_e32 v17, v2
	v_mov_b32_e32 v18, v2
	v_mov_b32_e32 v19, v2
	v_mov_b32_e32 v20, v2
	v_mov_b32_e32 v21, v2
	v_mov_b32_e32 v22, v2
	v_mov_b32_e32 v23, v2
	v_mov_b32_e32 v24, v2
	v_mov_b32_e32 v25, v2
	v_mov_b32_e32 v26, v2
	v_mov_b32_e32 v27, v2
	v_mov_b32_e32 v28, v2
	v_mov_b32_e32 v29, v2
	v_mov_b32_e32 v30, v2
	v_mov_b32_e32 v31, v2
	v_mov_b32_e32 v32, v2
	v_mov_b32_e32 v33, v2
	v_mov_b32_e32 v66, v2
	v_mov_b32_e32 v67, v2
	v_mov_b32_e32 v68, v2
	v_mov_b32_e32 v69, v2
	v_mov_b32_e32 v70, v2
	v_mov_b32_e32 v71, v2
	v_mov_b32_e32 v72, v2
	v_mov_b32_e32 v73, v2
	v_mov_b32_e32 v74, v2
	v_mov_b32_e32 v75, v2
	v_mov_b32_e32 v76, v2
	v_mov_b32_e32 v77, v2
	v_mov_b32_e32 v78, v2
	v_mov_b32_e32 v79, v2
	v_mov_b32_e32 v80, v2
	v_mov_b32_e32 v81, v2
	v_mov_b32_e32 v82, v2
	v_mov_b32_e32 v83, v2
	v_mov_b32_e32 v84, v2
	v_mov_b32_e32 v85, v2
	v_mov_b32_e32 v86, v2
	v_mov_b32_e32 v87, v2
	v_mov_b32_e32 v88, v2
	v_mov_b32_e32 v89, v2
	v_mov_b32_e32 v90, v2
	v_mov_b32_e32 v91, v2
	v_mov_b32_e32 v92, v2
	v_mov_b32_e32 v93, v2
	v_mov_b32_e32 v94, v2
	v_mov_b32_e32 v95, v2
	v_mov_b32_e32 v96, v2
	v_mov_b32_e32 v97, v2
	v_mov_b32_e32 v34, v2
	v_mov_b32_e32 v35, v2
	v_mov_b32_e32 v36, v2
	v_mov_b32_e32 v37, v2
	v_mov_b32_e32 v38, v2
	v_mov_b32_e32 v39, v2
	v_mov_b32_e32 v40, v2
	v_mov_b32_e32 v41, v2
	v_mov_b32_e32 v42, v2
	v_mov_b32_e32 v43, v2
	v_mov_b32_e32 v44, v2
	v_mov_b32_e32 v45, v2
	v_mov_b32_e32 v46, v2
	v_mov_b32_e32 v47, v2
	v_mov_b32_e32 v48, v2
	v_mov_b32_e32 v49, v2
	v_mov_b32_e32 v50, v2
	v_mov_b32_e32 v51, v2
	v_mov_b32_e32 v52, v2
	v_mov_b32_e32 v53, v2
	v_mov_b32_e32 v54, v2
	v_mov_b32_e32 v55, v2
	v_mov_b32_e32 v56, v2
	v_mov_b32_e32 v57, v2
	v_mov_b32_e32 v58, v2
	v_mov_b32_e32 v59, v2
	v_mov_b32_e32 v60, v2
	v_mov_b32_e32 v61, v2
	v_mov_b32_e32 v62, v2
	v_mov_b32_e32 v63, v2
	v_mov_b32_e32 v64, v2
	v_mov_b32_e32 v65, v2
	v_mov_b32_e32 v98, v2
	v_mov_b32_e32 v99, v2
	v_mov_b32_e32 v100, v2
	v_mov_b32_e32 v101, v2
	v_mov_b32_e32 v102, v2
	v_mov_b32_e32 v103, v2
	v_mov_b32_e32 v104, v2
	v_mov_b32_e32 v105, v2
	v_mov_b32_e32 v106, v2
	v_mov_b32_e32 v107, v2
	v_mov_b32_e32 v108, v2
	v_mov_b32_e32 v109, v2
	v_mov_b32_e32 v110, v2
	v_mov_b32_e32 v111, v2
	v_mov_b32_e32 v112, v2
	v_mov_b32_e32 v113, v2
	v_mov_b32_e32 v114, v2
	v_mov_b32_e32 v115, v2
	v_mov_b32_e32 v116, v2
	v_mov_b32_e32 v117, v2
	v_mov_b32_e32 v118, v2
	v_mov_b32_e32 v119, v2
	v_mov_b32_e32 v120, v2
	v_mov_b32_e32 v121, v2
	v_mov_b32_e32 v122, v2
	v_mov_b32_e32 v123, v2
	v_mov_b32_e32 v124, v2
	v_mov_b32_e32 v125, v2
	v_mov_b32_e32 v126, v2
	v_mov_b32_e32 v127, v2
	v_mov_b32_e32 v128, v2
	v_mov_b32_e32 v129, v2
	v_cmp_gt_u32_e32 vcc, 0x100, v1
	s_cbranch_vccz .Lkprio_4
	s_setprio 1
.Lkprio_4:
.LBB0_1254:
	ds_read_b128 v[130:133], v167
	ds_read_b128 v[134:137], v167 offset:1024
	ds_read_b128 v[156:159], v167 offset:2048
	ds_read_b128 v[160:163], v167 offset:3072
	ds_read_b128 v[170:173], v168
	ds_read_b128 v[174:177], v168 offset:1024
	ds_read_b128 v[178:181], v168 offset:2048
	ds_read_b128 v[182:185], v168 offset:3072
	s_add_u32 s14, s12, 0xfffc0080
	s_addc_u32 s15, s13, -1
	s_cmp_eq_u32 s39, 12
	s_cselect_b32 s17, s9, s15
	s_cselect_b32 s16, s8, s14
	s_cselect_b32 s15, s11, s19
	s_cselect_b32 s14, s10, s7
	v_lshl_add_u64 v[218:219], s[12:13], 0, v[148:149]
	s_add_i32 m0, s51, 0xc000
	ds_read_b128 v[186:189], v169
	ds_read_b128 v[190:193], v169 offset:1024
	ds_read_b128 v[194:197], v169 offset:2048
	ds_read_b128 v[198:201], v169 offset:3072
	ds_read_b128 v[202:205], v169 offset:4096
	ds_read_b128 v[206:209], v169 offset:5120
	ds_read_b128 v[210:213], v169 offset:6144
	ds_read_b128 v[214:217], v169 offset:7168
	global_load_lds_dwordx4 v[218:219], off
	v_lshl_add_u64 v[218:219], s[12:13], 0, v[150:151]
	s_add_i32 m0, s51, 0xe000
	s_nop 0
	global_load_lds_dwordx4 v[218:219], off
	s_waitcnt vmcnt(8)
	s_waitcnt lgkmcnt(0)
	s_barrier
	s_waitcnt lgkmcnt(0)
	v_mfma_f32_16x16x32_bf16 v[126:129], v[130:133], v[186:189], v[126:129]
	v_mfma_f32_16x16x32_bf16 v[122:125], v[156:159], v[186:189], v[122:125]
	v_mfma_f32_16x16x32_bf16 v[118:121], v[130:133], v[194:197], v[118:121]
	v_mfma_f32_16x16x32_bf16 v[114:117], v[156:159], v[194:197], v[114:117]
	v_mfma_f32_16x16x32_bf16 v[110:113], v[130:133], v[202:205], v[110:113]
	v_mfma_f32_16x16x32_bf16 v[106:109], v[156:159], v[202:205], v[106:109]
	v_mfma_f32_16x16x32_bf16 v[102:105], v[130:133], v[210:213], v[102:105]
	v_mfma_f32_16x16x32_bf16 v[98:101], v[156:159], v[210:213], v[98:101]
	v_mfma_f32_16x16x32_bf16 v[126:129], v[134:137], v[190:193], v[126:129]
	v_mfma_f32_16x16x32_bf16 v[122:125], v[160:163], v[190:193], v[122:125]
	v_mfma_f32_16x16x32_bf16 v[118:121], v[134:137], v[198:201], v[118:121]
	v_mfma_f32_16x16x32_bf16 v[114:117], v[160:163], v[198:201], v[114:117]
	v_mfma_f32_16x16x32_bf16 v[110:113], v[134:137], v[206:209], v[110:113]
	v_mfma_f32_16x16x32_bf16 v[106:109], v[160:163], v[206:209], v[106:109]
	v_mfma_f32_16x16x32_bf16 v[102:105], v[134:137], v[214:217], v[102:105]
	v_mfma_f32_16x16x32_bf16 v[98:101], v[160:163], v[214:217], v[98:101]
	v_mfma_f32_16x16x32_bf16 v[62:65], v[170:173], v[186:189], v[62:65]
	v_mfma_f32_16x16x32_bf16 v[58:61], v[178:181], v[186:189], v[58:61]
	v_mfma_f32_16x16x32_bf16 v[54:57], v[170:173], v[194:197], v[54:57]
	v_mfma_f32_16x16x32_bf16 v[50:53], v[178:181], v[194:197], v[50:53]
	v_mfma_f32_16x16x32_bf16 v[46:49], v[170:173], v[202:205], v[46:49]
	v_mfma_f32_16x16x32_bf16 v[42:45], v[178:181], v[202:205], v[42:45]
	v_mfma_f32_16x16x32_bf16 v[38:41], v[170:173], v[210:213], v[38:41]
	v_mfma_f32_16x16x32_bf16 v[34:37], v[178:181], v[210:213], v[34:37]
	v_mfma_f32_16x16x32_bf16 v[62:65], v[174:177], v[190:193], v[62:65]
	v_mfma_f32_16x16x32_bf16 v[58:61], v[182:185], v[190:193], v[58:61]
	v_mfma_f32_16x16x32_bf16 v[54:57], v[174:177], v[198:201], v[54:57]
	v_mfma_f32_16x16x32_bf16 v[50:53], v[182:185], v[198:201], v[50:53]
	v_mfma_f32_16x16x32_bf16 v[46:49], v[174:177], v[206:209], v[46:49]
	v_mfma_f32_16x16x32_bf16 v[42:45], v[182:185], v[206:209], v[42:45]
	v_mfma_f32_16x16x32_bf16 v[38:41], v[174:177], v[214:217], v[38:41]
	v_mfma_f32_16x16x32_bf16 v[34:37], v[182:185], v[214:217], v[34:37]
	s_barrier
	s_add_i32 s41, s74, s50
	v_lshl_add_u64 v[218:219], s[14:15], 0, v[140:141]
	s_mov_b32 m0, s41
	ds_read_b128 v[186:189], v169 offset:16384
	ds_read_b128 v[190:193], v169 offset:17408
	ds_read_b128 v[194:197], v169 offset:18432
	ds_read_b128 v[198:201], v169 offset:19456
	ds_read_b128 v[202:205], v169 offset:20480
	ds_read_b128 v[206:209], v169 offset:21504
	ds_read_b128 v[210:213], v169 offset:22528
	ds_read_b128 v[214:217], v169 offset:23552
	global_load_lds_dwordx4 v[218:219], off
	s_add_i32 m0, s41, 0x2000
	s_add_u32 s44, s14, 0x40000
	v_lshl_add_u64 v[220:221], s[14:15], 0, v[144:145]
	s_addc_u32 s45, s15, 0
	s_add_i32 s41, s75, s50
	global_load_lds_dwordx4 v[220:221], off
	v_lshl_add_u64 v[222:223], s[44:45], 0, v[140:141]
	s_mov_b32 m0, s41
	v_lshl_add_u64 v[224:225], s[16:17], 0, v[142:143]
	global_load_lds_dwordx4 v[222:223], off
	v_lshl_add_u64 v[222:223], s[44:45], 0, v[144:145]
	s_add_i32 m0, s41, 0x2000
	s_nop 0
	global_load_lds_dwordx4 v[222:223], off
	v_lshl_add_u64 v[222:223], s[16:17], 0, v[138:139]
	s_mov_b32 m0, s51
	s_nop 0
	global_load_lds_dwordx4 v[222:223], off
	s_mov_b32 m0, s52
	s_nop 0
	global_load_lds_dwordx4 v[224:225], off
	s_waitcnt vmcnt(8)
	s_waitcnt lgkmcnt(0)
	s_barrier
	s_waitcnt lgkmcnt(0)
	v_mfma_f32_16x16x32_bf16 v[94:97], v[130:133], v[186:189], v[94:97]
	v_mfma_f32_16x16x32_bf16 v[90:93], v[156:159], v[186:189], v[90:93]
	v_mfma_f32_16x16x32_bf16 v[86:89], v[130:133], v[194:197], v[86:89]
	v_mfma_f32_16x16x32_bf16 v[82:85], v[156:159], v[194:197], v[82:85]
	v_mfma_f32_16x16x32_bf16 v[78:81], v[130:133], v[202:205], v[78:81]
	v_mfma_f32_16x16x32_bf16 v[74:77], v[156:159], v[202:205], v[74:77]
	v_mfma_f32_16x16x32_bf16 v[70:73], v[130:133], v[210:213], v[70:73]
	v_mfma_f32_16x16x32_bf16 v[66:69], v[156:159], v[210:213], v[66:69]
	v_mfma_f32_16x16x32_bf16 v[94:97], v[134:137], v[190:193], v[94:97]
	v_mfma_f32_16x16x32_bf16 v[90:93], v[160:163], v[190:193], v[90:93]
	v_mfma_f32_16x16x32_bf16 v[86:89], v[134:137], v[198:201], v[86:89]
	v_mfma_f32_16x16x32_bf16 v[82:85], v[160:163], v[198:201], v[82:85]
	v_mfma_f32_16x16x32_bf16 v[78:81], v[134:137], v[206:209], v[78:81]
	v_mfma_f32_16x16x32_bf16 v[74:77], v[160:163], v[206:209], v[74:77]
	v_mfma_f32_16x16x32_bf16 v[70:73], v[134:137], v[214:217], v[70:73]
	v_mfma_f32_16x16x32_bf16 v[66:69], v[160:163], v[214:217], v[66:69]
	v_mfma_f32_16x16x32_bf16 v[30:33], v[170:173], v[186:189], v[30:33]
	v_mfma_f32_16x16x32_bf16 v[26:29], v[178:181], v[186:189], v[26:29]
	v_mfma_f32_16x16x32_bf16 v[22:25], v[170:173], v[194:197], v[22:25]
	v_mfma_f32_16x16x32_bf16 v[18:21], v[178:181], v[194:197], v[18:21]
	v_mfma_f32_16x16x32_bf16 v[14:17], v[170:173], v[202:205], v[14:17]
	v_mfma_f32_16x16x32_bf16 v[10:13], v[178:181], v[202:205], v[10:13]
	v_mfma_f32_16x16x32_bf16 v[6:9], v[170:173], v[210:213], v[6:9]
	v_mfma_f32_16x16x32_bf16 v[2:5], v[178:181], v[210:213], v[2:5]
	v_mfma_f32_16x16x32_bf16 v[30:33], v[174:177], v[190:193], v[30:33]
	v_mfma_f32_16x16x32_bf16 v[26:29], v[182:185], v[190:193], v[26:29]
	v_mfma_f32_16x16x32_bf16 v[22:25], v[174:177], v[198:201], v[22:25]
	v_mfma_f32_16x16x32_bf16 v[18:21], v[182:185], v[198:201], v[18:21]
	v_mfma_f32_16x16x32_bf16 v[14:17], v[174:177], v[206:209], v[14:17]
	v_mfma_f32_16x16x32_bf16 v[10:13], v[182:185], v[206:209], v[10:13]
	v_mfma_f32_16x16x32_bf16 v[6:9], v[174:177], v[214:217], v[6:9]
	v_mfma_f32_16x16x32_bf16 v[2:5], v[182:185], v[214:217], v[2:5]
	s_barrier
	s_add_i32 s41, 0, 0x18000
	v_add_u32_e32 v146, s41, v165
	s_add_i32 s44, 0, 0x1c000
	ds_read_b128 v[130:133], v146
	ds_read_b128 v[134:137], v146 offset:1024
	ds_read_b128 v[156:159], v146 offset:2048
	ds_read_b128 v[160:163], v146 offset:3072
	v_add_u32_e32 v146, s44, v165
	ds_read_b128 v[170:173], v146
	ds_read_b128 v[174:177], v146 offset:1024
	ds_read_b128 v[178:181], v146 offset:2048
	ds_read_b128 v[182:185], v146 offset:3072
	s_add_u32 s16, s16, 0x40000
	s_addc_u32 s17, s17, 0
	s_mov_b32 m0, s53
	v_lshl_add_u64 v[226:227], s[16:17], 0, v[138:139]
	ds_read_b128 v[186:189], v169 offset:32768
	ds_read_b128 v[190:193], v169 offset:33792
	ds_read_b128 v[194:197], v169 offset:34816
	ds_read_b128 v[198:201], v169 offset:35840
	ds_read_b128 v[202:205], v169 offset:36864
	ds_read_b128 v[206:209], v169 offset:37888
	ds_read_b128 v[210:213], v169 offset:38912
	ds_read_b128 v[214:217], v169 offset:39936
	global_load_lds_dwordx4 v[226:227], off
	v_lshl_add_u64 v[226:227], s[16:17], 0, v[142:143]
	s_mov_b32 m0, s54
	s_nop 0
	global_load_lds_dwordx4 v[226:227], off
	s_waitcnt vmcnt(8)
	s_waitcnt lgkmcnt(0)
	s_barrier
	s_waitcnt lgkmcnt(0)
	v_mfma_f32_16x16x32_bf16 v[126:129], v[130:133], v[186:189], v[126:129]
	v_mfma_f32_16x16x32_bf16 v[122:125], v[156:159], v[186:189], v[122:125]
	v_mfma_f32_16x16x32_bf16 v[118:121], v[130:133], v[194:197], v[118:121]
	v_mfma_f32_16x16x32_bf16 v[114:117], v[156:159], v[194:197], v[114:117]
	v_mfma_f32_16x16x32_bf16 v[110:113], v[130:133], v[202:205], v[110:113]
	v_mfma_f32_16x16x32_bf16 v[106:109], v[156:159], v[202:205], v[106:109]
	v_mfma_f32_16x16x32_bf16 v[102:105], v[130:133], v[210:213], v[102:105]
	v_mfma_f32_16x16x32_bf16 v[98:101], v[156:159], v[210:213], v[98:101]
	v_mfma_f32_16x16x32_bf16 v[126:129], v[134:137], v[190:193], v[126:129]
	v_mfma_f32_16x16x32_bf16 v[122:125], v[160:163], v[190:193], v[122:125]
	v_mfma_f32_16x16x32_bf16 v[118:121], v[134:137], v[198:201], v[118:121]
	v_mfma_f32_16x16x32_bf16 v[114:117], v[160:163], v[198:201], v[114:117]
	v_mfma_f32_16x16x32_bf16 v[110:113], v[134:137], v[206:209], v[110:113]
	v_mfma_f32_16x16x32_bf16 v[106:109], v[160:163], v[206:209], v[106:109]
	v_mfma_f32_16x16x32_bf16 v[102:105], v[134:137], v[214:217], v[102:105]
	v_mfma_f32_16x16x32_bf16 v[98:101], v[160:163], v[214:217], v[98:101]
	v_mfma_f32_16x16x32_bf16 v[62:65], v[170:173], v[186:189], v[62:65]
	v_mfma_f32_16x16x32_bf16 v[58:61], v[178:181], v[186:189], v[58:61]
	v_mfma_f32_16x16x32_bf16 v[54:57], v[170:173], v[194:197], v[54:57]
	v_mfma_f32_16x16x32_bf16 v[50:53], v[178:181], v[194:197], v[50:53]
	v_mfma_f32_16x16x32_bf16 v[46:49], v[170:173], v[202:205], v[46:49]
	v_mfma_f32_16x16x32_bf16 v[42:45], v[178:181], v[202:205], v[42:45]
	v_mfma_f32_16x16x32_bf16 v[38:41], v[170:173], v[210:213], v[38:41]
	v_mfma_f32_16x16x32_bf16 v[34:37], v[178:181], v[210:213], v[34:37]
	v_mfma_f32_16x16x32_bf16 v[62:65], v[174:177], v[190:193], v[62:65]
	v_mfma_f32_16x16x32_bf16 v[58:61], v[182:185], v[190:193], v[58:61]
	v_mfma_f32_16x16x32_bf16 v[54:57], v[174:177], v[198:201], v[54:57]
	v_mfma_f32_16x16x32_bf16 v[50:53], v[182:185], v[198:201], v[50:53]
	v_mfma_f32_16x16x32_bf16 v[46:49], v[174:177], v[206:209], v[46:49]
	v_mfma_f32_16x16x32_bf16 v[42:45], v[182:185], v[206:209], v[42:45]
	v_mfma_f32_16x16x32_bf16 v[38:41], v[174:177], v[214:217], v[38:41]
	v_mfma_f32_16x16x32_bf16 v[34:37], v[182:185], v[214:217], v[34:37]
	s_barrier
	s_add_i32 s16, s41, s50
	v_lshl_add_u64 v[218:219], v[218:219], 0, s[30:31]
	s_mov_b32 m0, s16
	ds_read_b128 v[186:189], v169 offset:49152
	ds_read_b128 v[190:193], v169 offset:50176
	ds_read_b128 v[194:197], v169 offset:51200
	ds_read_b128 v[198:201], v169 offset:52224
	ds_read_b128 v[202:205], v169 offset:53248
	ds_read_b128 v[206:209], v169 offset:54272
	ds_read_b128 v[210:213], v169 offset:55296
	ds_read_b128 v[214:217], v169 offset:56320
	global_load_lds_dwordx4 v[218:219], off
	s_add_i32 m0, s16, 0x2000
	s_add_u32 s14, s14, 0x40080
	v_lshl_add_u64 v[218:219], v[220:221], 0, s[30:31]
	s_addc_u32 s15, s15, 0
	s_add_i32 s16, s44, s50
	global_load_lds_dwordx4 v[218:219], off
	v_lshl_add_u64 v[218:219], s[14:15], 0, v[140:141]
	s_mov_b32 m0, s16
	s_nop 0
	global_load_lds_dwordx4 v[218:219], off
	v_lshl_add_u64 v[218:219], s[14:15], 0, v[144:145]
	s_add_i32 m0, s16, 0x2000
	s_nop 0
	global_load_lds_dwordx4 v[218:219], off
	v_lshl_add_u64 v[218:219], v[222:223], 0, s[30:31]
	s_mov_b32 m0, s61
	s_nop 0
	global_load_lds_dwordx4 v[218:219], off
	v_lshl_add_u64 v[218:219], v[224:225], 0, s[30:31]
	s_mov_b32 m0, s62
	s_nop 0
	global_load_lds_dwordx4 v[218:219], off
	s_waitcnt vmcnt(8)
	s_waitcnt lgkmcnt(0)
	s_barrier
	s_waitcnt lgkmcnt(0)
	v_mfma_f32_16x16x32_bf16 v[94:97], v[130:133], v[186:189], v[94:97]
	v_mfma_f32_16x16x32_bf16 v[90:93], v[156:159], v[186:189], v[90:93]
	v_mfma_f32_16x16x32_bf16 v[86:89], v[130:133], v[194:197], v[86:89]
	v_mfma_f32_16x16x32_bf16 v[82:85], v[156:159], v[194:197], v[82:85]
	v_mfma_f32_16x16x32_bf16 v[78:81], v[130:133], v[202:205], v[78:81]
	v_mfma_f32_16x16x32_bf16 v[74:77], v[156:159], v[202:205], v[74:77]
	v_mfma_f32_16x16x32_bf16 v[70:73], v[130:133], v[210:213], v[70:73]
	v_mfma_f32_16x16x32_bf16 v[66:69], v[156:159], v[210:213], v[66:69]
	v_mfma_f32_16x16x32_bf16 v[94:97], v[134:137], v[190:193], v[94:97]
	v_mfma_f32_16x16x32_bf16 v[90:93], v[160:163], v[190:193], v[90:93]
	v_mfma_f32_16x16x32_bf16 v[86:89], v[134:137], v[198:201], v[86:89]
	v_mfma_f32_16x16x32_bf16 v[82:85], v[160:163], v[198:201], v[82:85]
	v_mfma_f32_16x16x32_bf16 v[78:81], v[134:137], v[206:209], v[78:81]
	v_mfma_f32_16x16x32_bf16 v[74:77], v[160:163], v[206:209], v[74:77]
	v_mfma_f32_16x16x32_bf16 v[70:73], v[134:137], v[214:217], v[70:73]
	v_mfma_f32_16x16x32_bf16 v[66:69], v[160:163], v[214:217], v[66:69]
	v_mfma_f32_16x16x32_bf16 v[30:33], v[170:173], v[186:189], v[30:33]
	v_mfma_f32_16x16x32_bf16 v[26:29], v[178:181], v[186:189], v[26:29]
	v_mfma_f32_16x16x32_bf16 v[22:25], v[170:173], v[194:197], v[22:25]
	v_mfma_f32_16x16x32_bf16 v[18:21], v[178:181], v[194:197], v[18:21]
	v_mfma_f32_16x16x32_bf16 v[14:17], v[170:173], v[202:205], v[14:17]
	v_mfma_f32_16x16x32_bf16 v[10:13], v[178:181], v[202:205], v[10:13]
	v_mfma_f32_16x16x32_bf16 v[6:9], v[170:173], v[210:213], v[6:9]
	v_mfma_f32_16x16x32_bf16 v[2:5], v[178:181], v[210:213], v[2:5]
	v_mfma_f32_16x16x32_bf16 v[30:33], v[174:177], v[190:193], v[30:33]
	v_mfma_f32_16x16x32_bf16 v[26:29], v[182:185], v[190:193], v[26:29]
	v_mfma_f32_16x16x32_bf16 v[22:25], v[174:177], v[198:201], v[22:25]
	v_mfma_f32_16x16x32_bf16 v[18:21], v[182:185], v[198:201], v[18:21]
	v_mfma_f32_16x16x32_bf16 v[14:17], v[174:177], v[206:209], v[14:17]
	v_mfma_f32_16x16x32_bf16 v[10:13], v[182:185], v[206:209], v[10:13]
	v_mfma_f32_16x16x32_bf16 v[6:9], v[174:177], v[214:217], v[6:9]
	v_mfma_f32_16x16x32_bf16 v[2:5], v[182:185], v[214:217], v[2:5]
	s_barrier
	s_add_i32 s39, s39, 2
	s_add_u32 s12, s12, 0x100
	s_addc_u32 s13, s13, 0
	s_add_u32 s7, s7, 0x100
	s_addc_u32 s19, s19, 0
	s_cmp_gt_u32 s39, 13
	s_cbranch_scc0 .LBB0_1254
	s_setprio 0
	s_and_b64 vcc, exec, s[34:35]
	s_cbranch_vccz .LBB0_1257
	s_barrier

.LBB0_1448:
	s_add_u32 s30, s30, 0x40080
	s_addc_u32 s31, s31, 0
	s_add_u32 s17, s34, 0x100
	v_mov_b32_e32 v2, 0
	s_addc_u32 s19, s35, 0
	s_mov_b32 s45, -2
	v_mov_b32_e32 v3, v2
	v_mov_b32_e32 v4, v2
	v_mov_b32_e32 v5, v2
	v_mov_b32_e32 v6, v2
	v_mov_b32_e32 v7, v2
	v_mov_b32_e32 v8, v2
	v_mov_b32_e32 v9, v2
	v_mov_b32_e32 v18, v2
	v_mov_b32_e32 v19, v2
	v_mov_b32_e32 v20, v2
	v_mov_b32_e32 v21, v2
	v_mov_b32_e32 v22, v2
	v_mov_b32_e32 v23, v2
	v_mov_b32_e32 v24, v2
	v_mov_b32_e32 v25, v2
	v_mov_b32_e32 v34, v2
	v_mov_b32_e32 v35, v2
	v_mov_b32_e32 v36, v2
	v_mov_b32_e32 v37, v2
	v_mov_b32_e32 v38, v2
	v_mov_b32_e32 v39, v2
	v_mov_b32_e32 v40, v2
	v_mov_b32_e32 v41, v2
	v_mov_b32_e32 v50, v2
	v_mov_b32_e32 v51, v2
	v_mov_b32_e32 v52, v2
	v_mov_b32_e32 v53, v2
	v_mov_b32_e32 v54, v2
	v_mov_b32_e32 v55, v2
	v_mov_b32_e32 v56, v2
	v_mov_b32_e32 v57, v2
	v_mov_b32_e32 v10, v2
	v_mov_b32_e32 v11, v2
	v_mov_b32_e32 v12, v2
	v_mov_b32_e32 v13, v2
	v_mov_b32_e32 v14, v2
	v_mov_b32_e32 v15, v2
	v_mov_b32_e32 v16, v2
	v_mov_b32_e32 v17, v2
	v_mov_b32_e32 v26, v2
	v_mov_b32_e32 v27, v2
	v_mov_b32_e32 v28, v2
	v_mov_b32_e32 v29, v2
	v_mov_b32_e32 v30, v2
	v_mov_b32_e32 v31, v2
	v_mov_b32_e32 v32, v2
	v_mov_b32_e32 v33, v2
	v_mov_b32_e32 v42, v2
	v_mov_b32_e32 v43, v2
	v_mov_b32_e32 v44, v2
	v_mov_b32_e32 v45, v2
	v_mov_b32_e32 v46, v2
	v_mov_b32_e32 v47, v2
	v_mov_b32_e32 v48, v2
	v_mov_b32_e32 v49, v2
	v_mov_b32_e32 v58, v2
	v_mov_b32_e32 v59, v2
	v_mov_b32_e32 v60, v2
	v_mov_b32_e32 v61, v2
	v_mov_b32_e32 v62, v2
	v_mov_b32_e32 v63, v2
	v_mov_b32_e32 v64, v2
	v_mov_b32_e32 v65, v2
	v_mov_b32_e32 v66, v2
	v_mov_b32_e32 v67, v2
	v_mov_b32_e32 v68, v2
	v_mov_b32_e32 v69, v2
	v_mov_b32_e32 v70, v2
	v_mov_b32_e32 v71, v2
	v_mov_b32_e32 v72, v2
	v_mov_b32_e32 v73, v2
	v_mov_b32_e32 v82, v2
	v_mov_b32_e32 v83, v2
	v_mov_b32_e32 v84, v2
	v_mov_b32_e32 v85, v2
	v_mov_b32_e32 v86, v2
	v_mov_b32_e32 v87, v2
	v_mov_b32_e32 v88, v2
	v_mov_b32_e32 v89, v2
	v_mov_b32_e32 v98, v2
	v_mov_b32_e32 v99, v2
	v_mov_b32_e32 v100, v2
	v_mov_b32_e32 v101, v2
	v_mov_b32_e32 v102, v2
	v_mov_b32_e32 v103, v2
	v_mov_b32_e32 v104, v2
	v_mov_b32_e32 v105, v2
	v_mov_b32_e32 v114, v2
	v_mov_b32_e32 v115, v2
	v_mov_b32_e32 v116, v2
	v_mov_b32_e32 v117, v2
	v_mov_b32_e32 v118, v2
	v_mov_b32_e32 v119, v2
	v_mov_b32_e32 v120, v2
	v_mov_b32_e32 v121, v2
	v_mov_b32_e32 v74, v2
	v_mov_b32_e32 v75, v2
	v_mov_b32_e32 v76, v2
	v_mov_b32_e32 v77, v2
	v_mov_b32_e32 v78, v2
	v_mov_b32_e32 v79, v2
	v_mov_b32_e32 v80, v2
	v_mov_b32_e32 v81, v2
	v_mov_b32_e32 v90, v2
	v_mov_b32_e32 v91, v2
	v_mov_b32_e32 v92, v2
	v_mov_b32_e32 v93, v2
	v_mov_b32_e32 v94, v2
	v_mov_b32_e32 v95, v2
	v_mov_b32_e32 v96, v2
	v_mov_b32_e32 v97, v2
	v_mov_b32_e32 v106, v2
	v_mov_b32_e32 v107, v2
	v_mov_b32_e32 v108, v2
	v_mov_b32_e32 v109, v2
	v_mov_b32_e32 v110, v2
	v_mov_b32_e32 v111, v2
	v_mov_b32_e32 v112, v2
	v_mov_b32_e32 v113, v2
	v_mov_b32_e32 v122, v2
	v_mov_b32_e32 v123, v2
	v_mov_b32_e32 v124, v2
	v_mov_b32_e32 v125, v2
	v_mov_b32_e32 v126, v2
	v_mov_b32_e32 v127, v2
	v_mov_b32_e32 v128, v2
	v_mov_b32_e32 v129, v2
	v_cmp_gt_u32_e32 vcc, 0x100, v1
	s_cbranch_vccz .Lkprio_5
	s_setprio 1
.Lkprio_5:
.LBB0_1449:
	ds_read_b128 v[154:157], v151
	ds_read_b128 v[158:161], v151 offset:1024
	ds_read_b128 v[162:165], v151 offset:2048
	ds_read_b128 v[166:169], v151 offset:3072
	ds_read_b128 v[170:173], v152
	ds_read_b128 v[174:177], v152 offset:1024
	ds_read_b128 v[178:181], v152 offset:2048
	ds_read_b128 v[182:185], v152 offset:3072
	s_add_u32 s34, s30, 0xfffc0080
	s_addc_u32 s35, s31, -1
	s_cmp_eq_u32 s45, 12
	s_cselect_b32 s37, s27, s35
	s_cselect_b32 s36, s26, s34
	s_cselect_b32 s35, s29, s19
	s_cselect_b32 s34, s28, s17
	v_lshl_add_u64 v[220:221], s[30:31], 0, v[138:139]
	s_add_i32 m0, s25, 0xc000
	ds_read_b128 v[186:189], v153
	ds_read_b128 v[190:193], v153 offset:1024
	ds_read_b128 v[194:197], v153 offset:2048
	ds_read_b128 v[198:201], v153 offset:3072
	ds_read_b128 v[202:205], v153 offset:4096
	ds_read_b128 v[208:211], v153 offset:5120
	ds_read_b128 v[212:215], v153 offset:6144
	ds_read_b128 v[216:219], v153 offset:7168
	global_load_lds_dwordx4 v[220:221], off
	v_lshl_add_u64 v[220:221], s[30:31], 0, v[140:141]
	s_add_i32 m0, s25, 0xe000
	s_nop 0
	global_load_lds_dwordx4 v[220:221], off
	s_waitcnt vmcnt(8)
	s_waitcnt lgkmcnt(0)
	s_barrier
	s_waitcnt lgkmcnt(0)
	v_mfma_f32_16x16x32_bf16 v[126:129], v[154:157], v[186:189], v[126:129]
	v_mfma_f32_16x16x32_bf16 v[122:125], v[162:165], v[186:189], v[122:125]
	v_mfma_f32_16x16x32_bf16 v[110:113], v[154:157], v[194:197], v[110:113]
	v_mfma_f32_16x16x32_bf16 v[106:109], v[162:165], v[194:197], v[106:109]
	v_mfma_f32_16x16x32_bf16 v[94:97], v[154:157], v[202:205], v[94:97]
	v_mfma_f32_16x16x32_bf16 v[90:93], v[162:165], v[202:205], v[90:93]
	v_mfma_f32_16x16x32_bf16 v[78:81], v[154:157], v[212:215], v[78:81]
	v_mfma_f32_16x16x32_bf16 v[74:77], v[162:165], v[212:215], v[74:77]
	v_mfma_f32_16x16x32_bf16 v[126:129], v[158:161], v[190:193], v[126:129]
	v_mfma_f32_16x16x32_bf16 v[122:125], v[166:169], v[190:193], v[122:125]
	v_mfma_f32_16x16x32_bf16 v[110:113], v[158:161], v[198:201], v[110:113]
	v_mfma_f32_16x16x32_bf16 v[106:109], v[166:169], v[198:201], v[106:109]
	v_mfma_f32_16x16x32_bf16 v[94:97], v[158:161], v[208:211], v[94:97]
	v_mfma_f32_16x16x32_bf16 v[90:93], v[166:169], v[208:211], v[90:93]
	v_mfma_f32_16x16x32_bf16 v[78:81], v[158:161], v[216:219], v[78:81]
	v_mfma_f32_16x16x32_bf16 v[74:77], v[166:169], v[216:219], v[74:77]
	v_mfma_f32_16x16x32_bf16 v[118:121], v[170:173], v[186:189], v[118:121]
	v_mfma_f32_16x16x32_bf16 v[114:117], v[178:181], v[186:189], v[114:117]
	v_mfma_f32_16x16x32_bf16 v[102:105], v[170:173], v[194:197], v[102:105]
	v_mfma_f32_16x16x32_bf16 v[98:101], v[178:181], v[194:197], v[98:101]
	v_mfma_f32_16x16x32_bf16 v[86:89], v[170:173], v[202:205], v[86:89]
	v_mfma_f32_16x16x32_bf16 v[82:85], v[178:181], v[202:205], v[82:85]
	v_mfma_f32_16x16x32_bf16 v[70:73], v[170:173], v[212:215], v[70:73]
	v_mfma_f32_16x16x32_bf16 v[66:69], v[178:181], v[212:215], v[66:69]
	v_mfma_f32_16x16x32_bf16 v[118:121], v[174:177], v[190:193], v[118:121]
	v_mfma_f32_16x16x32_bf16 v[114:117], v[182:185], v[190:193], v[114:117]
	v_mfma_f32_16x16x32_bf16 v[102:105], v[174:177], v[198:201], v[102:105]
	v_mfma_f32_16x16x32_bf16 v[98:101], v[182:185], v[198:201], v[98:101]
	v_mfma_f32_16x16x32_bf16 v[86:89], v[174:177], v[208:211], v[86:89]
	v_mfma_f32_16x16x32_bf16 v[82:85], v[182:185], v[208:211], v[82:85]
	v_mfma_f32_16x16x32_bf16 v[70:73], v[174:177], v[216:219], v[70:73]
	v_mfma_f32_16x16x32_bf16 v[66:69], v[182:185], v[216:219], v[66:69]
	s_barrier
	s_add_i32 s57, s54, s41
	v_lshl_add_u64 v[220:221], s[34:35], 0, v[132:133]
	s_mov_b32 m0, s57
	ds_read_b128 v[186:189], v153 offset:16384
	ds_read_b128 v[190:193], v153 offset:17408
	ds_read_b128 v[194:197], v153 offset:18432
	ds_read_b128 v[198:201], v153 offset:19456
	ds_read_b128 v[202:205], v153 offset:20480
	ds_read_b128 v[208:211], v153 offset:21504
	ds_read_b128 v[212:215], v153 offset:22528
	ds_read_b128 v[216:219], v153 offset:23552
	global_load_lds_dwordx4 v[220:221], off
	s_add_i32 m0, s57, 0x2000
	s_add_u32 s58, s34, 0x580000
	v_lshl_add_u64 v[222:223], s[34:35], 0, v[136:137]
	s_addc_u32 s59, s35, 0
	s_add_i32 s57, s55, s41
	global_load_lds_dwordx4 v[222:223], off
	v_lshl_add_u64 v[224:225], s[58:59], 0, v[132:133]
	s_mov_b32 m0, s57
	v_lshl_add_u64 v[226:227], s[36:37], 0, v[134:135]
	global_load_lds_dwordx4 v[224:225], off
	v_lshl_add_u64 v[224:225], s[58:59], 0, v[136:137]
	s_add_i32 m0, s57, 0x2000
	s_nop 0
	global_load_lds_dwordx4 v[224:225], off
	v_lshl_add_u64 v[224:225], s[36:37], 0, v[130:131]
	s_mov_b32 m0, s25
	s_nop 0
	global_load_lds_dwordx4 v[224:225], off
	s_mov_b32 m0, s46
	s_nop 0
	global_load_lds_dwordx4 v[226:227], off
	s_waitcnt vmcnt(8)
	s_waitcnt lgkmcnt(0)
	s_barrier
	s_waitcnt lgkmcnt(0)
	v_mfma_f32_16x16x32_bf16 v[62:65], v[154:157], v[186:189], v[62:65]
	v_mfma_f32_16x16x32_bf16 v[58:61], v[162:165], v[186:189], v[58:61]
	v_mfma_f32_16x16x32_bf16 v[46:49], v[154:157], v[194:197], v[46:49]
	v_mfma_f32_16x16x32_bf16 v[42:45], v[162:165], v[194:197], v[42:45]
	v_mfma_f32_16x16x32_bf16 v[30:33], v[154:157], v[202:205], v[30:33]
	v_mfma_f32_16x16x32_bf16 v[26:29], v[162:165], v[202:205], v[26:29]
	v_mfma_f32_16x16x32_bf16 v[14:17], v[154:157], v[212:215], v[14:17]
	v_mfma_f32_16x16x32_bf16 v[10:13], v[162:165], v[212:215], v[10:13]
	v_mfma_f32_16x16x32_bf16 v[62:65], v[158:161], v[190:193], v[62:65]
	v_mfma_f32_16x16x32_bf16 v[58:61], v[166:169], v[190:193], v[58:61]
	v_mfma_f32_16x16x32_bf16 v[46:49], v[158:161], v[198:201], v[46:49]
	v_mfma_f32_16x16x32_bf16 v[42:45], v[166:169], v[198:201], v[42:45]
	v_mfma_f32_16x16x32_bf16 v[30:33], v[158:161], v[208:211], v[30:33]
	v_mfma_f32_16x16x32_bf16 v[26:29], v[166:169], v[208:211], v[26:29]
	v_mfma_f32_16x16x32_bf16 v[14:17], v[158:161], v[216:219], v[14:17]
	v_mfma_f32_16x16x32_bf16 v[10:13], v[166:169], v[216:219], v[10:13]
	v_mfma_f32_16x16x32_bf16 v[54:57], v[170:173], v[186:189], v[54:57]
	v_mfma_f32_16x16x32_bf16 v[50:53], v[178:181], v[186:189], v[50:53]
	v_mfma_f32_16x16x32_bf16 v[38:41], v[170:173], v[194:197], v[38:41]
	v_mfma_f32_16x16x32_bf16 v[34:37], v[178:181], v[194:197], v[34:37]
	v_mfma_f32_16x16x32_bf16 v[22:25], v[170:173], v[202:205], v[22:25]
	v_mfma_f32_16x16x32_bf16 v[18:21], v[178:181], v[202:205], v[18:21]
	v_mfma_f32_16x16x32_bf16 v[6:9], v[170:173], v[212:215], v[6:9]
	v_mfma_f32_16x16x32_bf16 v[2:5], v[178:181], v[212:215], v[2:5]
	v_mfma_f32_16x16x32_bf16 v[54:57], v[174:177], v[190:193], v[54:57]
	v_mfma_f32_16x16x32_bf16 v[50:53], v[182:185], v[190:193], v[50:53]
	v_mfma_f32_16x16x32_bf16 v[38:41], v[174:177], v[198:201], v[38:41]
	v_mfma_f32_16x16x32_bf16 v[34:37], v[182:185], v[198:201], v[34:37]
	v_mfma_f32_16x16x32_bf16 v[22:25], v[174:177], v[208:211], v[22:25]
	v_mfma_f32_16x16x32_bf16 v[18:21], v[182:185], v[208:211], v[18:21]
	v_mfma_f32_16x16x32_bf16 v[6:9], v[174:177], v[216:219], v[6:9]
	v_mfma_f32_16x16x32_bf16 v[2:5], v[182:185], v[216:219], v[2:5]
	s_barrier
	s_add_i32 s57, 0, 0x18000
	s_add_i32 s58, 0, 0x1c000
	v_add_u32_e32 v166, s57, v149
	v_add_u32_e32 v182, s58, v149
	ds_read_b128 v[154:157], v166
	ds_read_b128 v[158:161], v166 offset:1024
	ds_read_b128 v[162:165], v166 offset:2048
	ds_read_b128 v[166:169], v166 offset:3072
	ds_read_b128 v[170:173], v182
	ds_read_b128 v[174:177], v182 offset:1024
	ds_read_b128 v[178:181], v182 offset:2048
	ds_read_b128 v[182:185], v182 offset:3072
	s_add_u32 s36, s36, 0x40000
	s_addc_u32 s37, s37, 0
	s_mov_b32 m0, s47
	v_lshl_add_u64 v[228:229], s[36:37], 0, v[130:131]
	ds_read_b128 v[186:189], v153 offset:32768
	ds_read_b128 v[190:193], v153 offset:33792
	ds_read_b128 v[194:197], v153 offset:34816
	ds_read_b128 v[198:201], v153 offset:35840
	ds_read_b128 v[202:205], v153 offset:36864
	ds_read_b128 v[208:211], v153 offset:37888
	ds_read_b128 v[212:215], v153 offset:38912
	ds_read_b128 v[216:219], v153 offset:39936
	global_load_lds_dwordx4 v[228:229], off
	v_lshl_add_u64 v[228:229], s[36:37], 0, v[134:135]
	s_mov_b32 m0, s48
	s_nop 0
	global_load_lds_dwordx4 v[228:229], off
	s_waitcnt vmcnt(8)
	s_waitcnt lgkmcnt(0)
	s_barrier
	s_waitcnt lgkmcnt(0)
	v_mfma_f32_16x16x32_bf16 v[126:129], v[154:157], v[186:189], v[126:129]
	v_mfma_f32_16x16x32_bf16 v[122:125], v[162:165], v[186:189], v[122:125]
	v_mfma_f32_16x16x32_bf16 v[110:113], v[154:157], v[194:197], v[110:113]
	v_mfma_f32_16x16x32_bf16 v[106:109], v[162:165], v[194:197], v[106:109]
	v_mfma_f32_16x16x32_bf16 v[94:97], v[154:157], v[202:205], v[94:97]
	v_mfma_f32_16x16x32_bf16 v[90:93], v[162:165], v[202:205], v[90:93]
	v_mfma_f32_16x16x32_bf16 v[78:81], v[154:157], v[212:215], v[78:81]
	v_mfma_f32_16x16x32_bf16 v[74:77], v[162:165], v[212:215], v[74:77]
	v_mfma_f32_16x16x32_bf16 v[126:129], v[158:161], v[190:193], v[126:129]
	v_mfma_f32_16x16x32_bf16 v[122:125], v[166:169], v[190:193], v[122:125]
	v_mfma_f32_16x16x32_bf16 v[110:113], v[158:161], v[198:201], v[110:113]
	v_mfma_f32_16x16x32_bf16 v[106:109], v[166:169], v[198:201], v[106:109]
	v_mfma_f32_16x16x32_bf16 v[94:97], v[158:161], v[208:211], v[94:97]
	v_mfma_f32_16x16x32_bf16 v[90:93], v[166:169], v[208:211], v[90:93]
	v_mfma_f32_16x16x32_bf16 v[78:81], v[158:161], v[216:219], v[78:81]
	v_mfma_f32_16x16x32_bf16 v[74:77], v[166:169], v[216:219], v[74:77]
	v_mfma_f32_16x16x32_bf16 v[118:121], v[170:173], v[186:189], v[118:121]
	v_mfma_f32_16x16x32_bf16 v[114:117], v[178:181], v[186:189], v[114:117]
	v_mfma_f32_16x16x32_bf16 v[102:105], v[170:173], v[194:197], v[102:105]
	v_mfma_f32_16x16x32_bf16 v[98:101], v[178:181], v[194:197], v[98:101]
	v_mfma_f32_16x16x32_bf16 v[86:89], v[170:173], v[202:205], v[86:89]
	v_mfma_f32_16x16x32_bf16 v[82:85], v[178:181], v[202:205], v[82:85]
	v_mfma_f32_16x16x32_bf16 v[70:73], v[170:173], v[212:215], v[70:73]
	v_mfma_f32_16x16x32_bf16 v[66:69], v[178:181], v[212:215], v[66:69]
	v_mfma_f32_16x16x32_bf16 v[118:121], v[174:177], v[190:193], v[118:121]
	v_mfma_f32_16x16x32_bf16 v[114:117], v[182:185], v[190:193], v[114:117]
	v_mfma_f32_16x16x32_bf16 v[102:105], v[174:177], v[198:201], v[102:105]
	v_mfma_f32_16x16x32_bf16 v[98:101], v[182:185], v[198:201], v[98:101]
	v_mfma_f32_16x16x32_bf16 v[86:89], v[174:177], v[208:211], v[86:89]
	v_mfma_f32_16x16x32_bf16 v[82:85], v[182:185], v[208:211], v[82:85]
	v_mfma_f32_16x16x32_bf16 v[70:73], v[174:177], v[216:219], v[70:73]
	v_mfma_f32_16x16x32_bf16 v[66:69], v[182:185], v[216:219], v[66:69]
	s_barrier
	s_add_i32 s36, s57, s41
	v_lshl_add_u64 v[220:221], v[220:221], 0, s[12:13]
	s_mov_b32 m0, s36
	ds_read_b128 v[186:189], v153 offset:49152
	ds_read_b128 v[190:193], v153 offset:50176
	ds_read_b128 v[194:197], v153 offset:51200
	ds_read_b128 v[198:201], v153 offset:52224
	ds_read_b128 v[202:205], v153 offset:53248
	ds_read_b128 v[208:211], v153 offset:54272
	ds_read_b128 v[212:215], v153 offset:55296
	ds_read_b128 v[216:219], v153 offset:56320
	global_load_lds_dwordx4 v[220:221], off
	s_add_i32 m0, s36, 0x2000
	s_add_u32 s34, s34, 0x580080
	v_lshl_add_u64 v[220:221], v[222:223], 0, s[12:13]
	s_addc_u32 s35, s35, 0
	s_add_i32 s36, s58, s41
	global_load_lds_dwordx4 v[220:221], off
	v_lshl_add_u64 v[220:221], s[34:35], 0, v[132:133]
	s_mov_b32 m0, s36
	s_nop 0
	global_load_lds_dwordx4 v[220:221], off
	v_lshl_add_u64 v[220:221], s[34:35], 0, v[136:137]
	s_add_i32 m0, s36, 0x2000
	s_nop 0
	global_load_lds_dwordx4 v[220:221], off
	v_lshl_add_u64 v[220:221], v[224:225], 0, s[12:13]
	s_mov_b32 m0, s51
	s_nop 0
	global_load_lds_dwordx4 v[220:221], off
	v_lshl_add_u64 v[220:221], v[226:227], 0, s[12:13]
	s_mov_b32 m0, s52
	s_nop 0
	global_load_lds_dwordx4 v[220:221], off
	s_waitcnt vmcnt(8)
	s_waitcnt lgkmcnt(0)
	s_barrier
	s_waitcnt lgkmcnt(0)
	v_mfma_f32_16x16x32_bf16 v[62:65], v[154:157], v[186:189], v[62:65]
	v_mfma_f32_16x16x32_bf16 v[58:61], v[162:165], v[186:189], v[58:61]
	v_mfma_f32_16x16x32_bf16 v[46:49], v[154:157], v[194:197], v[46:49]
	v_mfma_f32_16x16x32_bf16 v[42:45], v[162:165], v[194:197], v[42:45]
	v_mfma_f32_16x16x32_bf16 v[30:33], v[154:157], v[202:205], v[30:33]
	v_mfma_f32_16x16x32_bf16 v[26:29], v[162:165], v[202:205], v[26:29]
	v_mfma_f32_16x16x32_bf16 v[14:17], v[154:157], v[212:215], v[14:17]
	v_mfma_f32_16x16x32_bf16 v[10:13], v[162:165], v[212:215], v[10:13]
	v_mfma_f32_16x16x32_bf16 v[62:65], v[158:161], v[190:193], v[62:65]
	v_mfma_f32_16x16x32_bf16 v[58:61], v[166:169], v[190:193], v[58:61]
	v_mfma_f32_16x16x32_bf16 v[46:49], v[158:161], v[198:201], v[46:49]
	v_mfma_f32_16x16x32_bf16 v[42:45], v[166:169], v[198:201], v[42:45]
	v_mfma_f32_16x16x32_bf16 v[30:33], v[158:161], v[208:211], v[30:33]
	v_mfma_f32_16x16x32_bf16 v[26:29], v[166:169], v[208:211], v[26:29]
	v_mfma_f32_16x16x32_bf16 v[14:17], v[158:161], v[216:219], v[14:17]
	v_mfma_f32_16x16x32_bf16 v[10:13], v[166:169], v[216:219], v[10:13]
	v_mfma_f32_16x16x32_bf16 v[54:57], v[170:173], v[186:189], v[54:57]
	v_mfma_f32_16x16x32_bf16 v[50:53], v[178:181], v[186:189], v[50:53]
	v_mfma_f32_16x16x32_bf16 v[38:41], v[170:173], v[194:197], v[38:41]
	v_mfma_f32_16x16x32_bf16 v[34:37], v[178:181], v[194:197], v[34:37]
	v_mfma_f32_16x16x32_bf16 v[22:25], v[170:173], v[202:205], v[22:25]
	v_mfma_f32_16x16x32_bf16 v[18:21], v[178:181], v[202:205], v[18:21]
	v_mfma_f32_16x16x32_bf16 v[6:9], v[170:173], v[212:215], v[6:9]
	v_mfma_f32_16x16x32_bf16 v[2:5], v[178:181], v[212:215], v[2:5]
	v_mfma_f32_16x16x32_bf16 v[54:57], v[174:177], v[190:193], v[54:57]
	v_mfma_f32_16x16x32_bf16 v[50:53], v[182:185], v[190:193], v[50:53]
	v_mfma_f32_16x16x32_bf16 v[38:41], v[174:177], v[198:201], v[38:41]
	v_mfma_f32_16x16x32_bf16 v[34:37], v[182:185], v[198:201], v[34:37]
	v_mfma_f32_16x16x32_bf16 v[22:25], v[174:177], v[208:211], v[22:25]
	v_mfma_f32_16x16x32_bf16 v[18:21], v[182:185], v[208:211], v[18:21]
	v_mfma_f32_16x16x32_bf16 v[6:9], v[174:177], v[216:219], v[6:9]
	v_mfma_f32_16x16x32_bf16 v[2:5], v[182:185], v[216:219], v[2:5]
	s_barrier
	s_add_i32 s45, s45, 2
	s_add_u32 s30, s30, 0x100
	s_addc_u32 s31, s31, 0
	s_add_u32 s17, s17, 0x100
	s_addc_u32 s19, s19, 0
	s_cmp_gt_u32 s45, 13
	s_cbranch_scc0 .LBB0_1449
	s_setprio 0
	s_and_b64 vcc, exec, s[14:15]
	s_cbranch_vccz .LBB0_1452
	s_barrier

.LBB0_1540:
	s_add_u32 s38, s38, 0xb0080
	s_addc_u32 s39, s39, 0
	s_add_u32 s44, s40, 0x100
	v_mov_b32_e32 v2, 0
	s_addc_u32 s45, s41, 0
	s_mov_b32 s77, -2
	v_mov_b32_e32 v3, v2
	v_mov_b32_e32 v4, v2
	v_mov_b32_e32 v5, v2
	v_mov_b32_e32 v6, v2
	v_mov_b32_e32 v7, v2
	v_mov_b32_e32 v8, v2
	v_mov_b32_e32 v9, v2
	v_mov_b32_e32 v10, v2
	v_mov_b32_e32 v11, v2
	v_mov_b32_e32 v12, v2
	v_mov_b32_e32 v13, v2
	v_mov_b32_e32 v14, v2
	v_mov_b32_e32 v15, v2
	v_mov_b32_e32 v16, v2
	v_mov_b32_e32 v17, v2
	v_mov_b32_e32 v18, v2
	v_mov_b32_e32 v19, v2
	v_mov_b32_e32 v20, v2
	v_mov_b32_e32 v21, v2
	v_mov_b32_e32 v22, v2
	v_mov_b32_e32 v23, v2
	v_mov_b32_e32 v24, v2
	v_mov_b32_e32 v25, v2
	v_mov_b32_e32 v26, v2
	v_mov_b32_e32 v27, v2
	v_mov_b32_e32 v28, v2
	v_mov_b32_e32 v29, v2
	v_mov_b32_e32 v30, v2
	v_mov_b32_e32 v31, v2
	v_mov_b32_e32 v32, v2
	v_mov_b32_e32 v33, v2
	v_mov_b32_e32 v50, v2
	v_mov_b32_e32 v51, v2
	v_mov_b32_e32 v52, v2
	v_mov_b32_e32 v53, v2
	v_mov_b32_e32 v58, v2
	v_mov_b32_e32 v59, v2
	v_mov_b32_e32 v60, v2
	v_mov_b32_e32 v61, v2
	v_mov_b32_e32 v74, v2
	v_mov_b32_e32 v75, v2
	v_mov_b32_e32 v76, v2
	v_mov_b32_e32 v77, v2
	v_mov_b32_e32 v78, v2
	v_mov_b32_e32 v79, v2
	v_mov_b32_e32 v80, v2
	v_mov_b32_e32 v81, v2
	v_mov_b32_e32 v82, v2
	v_mov_b32_e32 v83, v2
	v_mov_b32_e32 v84, v2
	v_mov_b32_e32 v85, v2
	v_mov_b32_e32 v86, v2
	v_mov_b32_e32 v87, v2
	v_mov_b32_e32 v88, v2
	v_mov_b32_e32 v89, v2
	v_mov_b32_e32 v90, v2
	v_mov_b32_e32 v91, v2
	v_mov_b32_e32 v92, v2
	v_mov_b32_e32 v93, v2
	v_mov_b32_e32 v94, v2
	v_mov_b32_e32 v95, v2
	v_mov_b32_e32 v96, v2
	v_mov_b32_e32 v97, v2
	v_mov_b32_e32 v34, v2
	v_mov_b32_e32 v35, v2
	v_mov_b32_e32 v36, v2
	v_mov_b32_e32 v37, v2
	v_mov_b32_e32 v38, v2
	v_mov_b32_e32 v39, v2
	v_mov_b32_e32 v40, v2
	v_mov_b32_e32 v41, v2
	v_mov_b32_e32 v42, v2
	v_mov_b32_e32 v43, v2
	v_mov_b32_e32 v44, v2
	v_mov_b32_e32 v45, v2
	v_mov_b32_e32 v46, v2
	v_mov_b32_e32 v47, v2
	v_mov_b32_e32 v48, v2
	v_mov_b32_e32 v49, v2
	v_mov_b32_e32 v54, v2
	v_mov_b32_e32 v55, v2
	v_mov_b32_e32 v56, v2
	v_mov_b32_e32 v57, v2
	v_mov_b32_e32 v62, v2
	v_mov_b32_e32 v63, v2
	v_mov_b32_e32 v64, v2
	v_mov_b32_e32 v65, v2
	v_mov_b32_e32 v66, v2
	v_mov_b32_e32 v67, v2
	v_mov_b32_e32 v68, v2
	v_mov_b32_e32 v69, v2
	v_mov_b32_e32 v70, v2
	v_mov_b32_e32 v71, v2
	v_mov_b32_e32 v72, v2
	v_mov_b32_e32 v73, v2
	v_mov_b32_e32 v98, v2
	v_mov_b32_e32 v99, v2
	v_mov_b32_e32 v100, v2
	v_mov_b32_e32 v101, v2
	v_mov_b32_e32 v102, v2
	v_mov_b32_e32 v103, v2
	v_mov_b32_e32 v104, v2
	v_mov_b32_e32 v105, v2
	v_mov_b32_e32 v106, v2
	v_mov_b32_e32 v107, v2
	v_mov_b32_e32 v108, v2
	v_mov_b32_e32 v109, v2
	v_mov_b32_e32 v110, v2
	v_mov_b32_e32 v111, v2
	v_mov_b32_e32 v112, v2
	v_mov_b32_e32 v113, v2
	v_mov_b32_e32 v114, v2
	v_mov_b32_e32 v115, v2
	v_mov_b32_e32 v116, v2
	v_mov_b32_e32 v117, v2
	v_mov_b32_e32 v118, v2
	v_mov_b32_e32 v119, v2
	v_mov_b32_e32 v120, v2
	v_mov_b32_e32 v121, v2
	v_mov_b32_e32 v122, v2
	v_mov_b32_e32 v123, v2
	v_mov_b32_e32 v124, v2
	v_mov_b32_e32 v125, v2
	v_mov_b32_e32 v126, v2
	v_mov_b32_e32 v127, v2
	v_mov_b32_e32 v128, v2
	v_mov_b32_e32 v129, v2
	v_cmp_gt_u32_e32 vcc, 0x100, v1
	s_cbranch_vccz .Lkprio_6
	s_setprio 1
.Lkprio_6:
.LBB0_1541:
	ds_read_b128 v[130:133], v210
	ds_read_b128 v[134:137], v210 offset:1024
	ds_read_b128 v[138:141], v210 offset:2048
	ds_read_b128 v[142:145], v210 offset:3072
	ds_read_b128 v[146:149], v211
	ds_read_b128 v[150:153], v211 offset:1024
	ds_read_b128 v[154:157], v211 offset:2048
	ds_read_b128 v[158:161], v211 offset:3072
	s_add_u32 s40, s38, 0xfff50080
	s_addc_u32 s41, s39, -1
	s_cmp_eq_u32 s77, 40
	s_cselect_b32 s43, s35, s41
	s_cselect_b32 s42, s34, s40
	s_cselect_b32 s41, s37, s45
	s_cselect_b32 s40, s36, s44
	v_lshl_add_u64 v[218:219], s[38:39], 0, v[178:179]
	s_add_i32 m0, s50, 0xc000
	ds_read_b128 v[162:165], v212
	ds_read_b128 v[166:169], v212 offset:1024
	ds_read_b128 v[186:189], v212 offset:2048
	ds_read_b128 v[190:193], v212 offset:3072
	ds_read_b128 v[194:197], v212 offset:4096
	ds_read_b128 v[198:201], v212 offset:5120
	ds_read_b128 v[202:205], v212 offset:6144
	ds_read_b128 v[214:217], v212 offset:7168
	global_load_lds_dwordx4 v[218:219], off
	v_lshl_add_u64 v[218:219], s[38:39], 0, v[180:181]
	s_add_i32 m0, s50, 0xe000
	s_nop 0
	global_load_lds_dwordx4 v[218:219], off
	s_waitcnt vmcnt(8)
	s_waitcnt lgkmcnt(0)
	s_barrier
	s_waitcnt lgkmcnt(0)
	v_mfma_f32_16x16x32_bf16 v[126:129], v[130:133], v[162:165], v[126:129]
	v_mfma_f32_16x16x32_bf16 v[122:125], v[138:141], v[162:165], v[122:125]
	v_mfma_f32_16x16x32_bf16 v[118:121], v[130:133], v[186:189], v[118:121]
	v_mfma_f32_16x16x32_bf16 v[114:117], v[138:141], v[186:189], v[114:117]
	v_mfma_f32_16x16x32_bf16 v[110:113], v[130:133], v[194:197], v[110:113]
	v_mfma_f32_16x16x32_bf16 v[106:109], v[138:141], v[194:197], v[106:109]
	v_mfma_f32_16x16x32_bf16 v[102:105], v[130:133], v[202:205], v[102:105]
	v_mfma_f32_16x16x32_bf16 v[98:101], v[138:141], v[202:205], v[98:101]
	v_mfma_f32_16x16x32_bf16 v[126:129], v[134:137], v[166:169], v[126:129]
	v_mfma_f32_16x16x32_bf16 v[122:125], v[142:145], v[166:169], v[122:125]
	v_mfma_f32_16x16x32_bf16 v[118:121], v[134:137], v[190:193], v[118:121]
	v_mfma_f32_16x16x32_bf16 v[114:117], v[142:145], v[190:193], v[114:117]
	v_mfma_f32_16x16x32_bf16 v[110:113], v[134:137], v[198:201], v[110:113]
	v_mfma_f32_16x16x32_bf16 v[106:109], v[142:145], v[198:201], v[106:109]
	v_mfma_f32_16x16x32_bf16 v[102:105], v[134:137], v[214:217], v[102:105]
	v_mfma_f32_16x16x32_bf16 v[98:101], v[142:145], v[214:217], v[98:101]
	v_mfma_f32_16x16x32_bf16 v[70:73], v[146:149], v[162:165], v[70:73]
	v_mfma_f32_16x16x32_bf16 v[66:69], v[154:157], v[162:165], v[66:69]
	v_mfma_f32_16x16x32_bf16 v[62:65], v[146:149], v[186:189], v[62:65]
	v_mfma_f32_16x16x32_bf16 v[54:57], v[154:157], v[186:189], v[54:57]
	v_mfma_f32_16x16x32_bf16 v[46:49], v[146:149], v[194:197], v[46:49]
	v_mfma_f32_16x16x32_bf16 v[42:45], v[154:157], v[194:197], v[42:45]
	v_mfma_f32_16x16x32_bf16 v[38:41], v[146:149], v[202:205], v[38:41]
	v_mfma_f32_16x16x32_bf16 v[34:37], v[154:157], v[202:205], v[34:37]
	v_mfma_f32_16x16x32_bf16 v[70:73], v[150:153], v[166:169], v[70:73]
	v_mfma_f32_16x16x32_bf16 v[66:69], v[158:161], v[166:169], v[66:69]
	v_mfma_f32_16x16x32_bf16 v[62:65], v[150:153], v[190:193], v[62:65]
	v_mfma_f32_16x16x32_bf16 v[54:57], v[158:161], v[190:193], v[54:57]
	v_mfma_f32_16x16x32_bf16 v[46:49], v[150:153], v[198:201], v[46:49]
	v_mfma_f32_16x16x32_bf16 v[42:45], v[158:161], v[198:201], v[42:45]
	v_mfma_f32_16x16x32_bf16 v[38:41], v[150:153], v[214:217], v[38:41]
	v_mfma_f32_16x16x32_bf16 v[34:37], v[158:161], v[214:217], v[34:37]
	s_barrier
	s_add_i32 s78, s61, s48
	v_lshl_add_u64 v[218:219], s[40:41], 0, v[172:173]
	s_mov_b32 m0, s78
	ds_read_b128 v[162:165], v212 offset:16384
	ds_read_b128 v[166:169], v212 offset:17408
	ds_read_b128 v[186:189], v212 offset:18432
	ds_read_b128 v[190:193], v212 offset:19456
	ds_read_b128 v[194:197], v212 offset:20480
	ds_read_b128 v[198:201], v212 offset:21504
	ds_read_b128 v[202:205], v212 offset:22528
	ds_read_b128 v[214:217], v212 offset:23552
	global_load_lds_dwordx4 v[218:219], off
	s_add_i32 m0, s78, 0x2000
	s_add_u32 s78, s40, 0xb0000
	v_lshl_add_u64 v[220:221], s[40:41], 0, v[176:177]
	s_addc_u32 s79, s41, 0
	s_add_i32 s80, s62, s48
	global_load_lds_dwordx4 v[220:221], off
	v_lshl_add_u64 v[222:223], s[78:79], 0, v[172:173]
	s_mov_b32 m0, s80
	v_lshl_add_u64 v[224:225], s[42:43], 0, v[174:175]
	global_load_lds_dwordx4 v[222:223], off
	v_lshl_add_u64 v[222:223], s[78:79], 0, v[176:177]
	s_add_i32 m0, s80, 0x2000
	s_nop 0
	global_load_lds_dwordx4 v[222:223], off
	v_lshl_add_u64 v[222:223], s[42:43], 0, v[170:171]
	s_mov_b32 m0, s50
	s_nop 0
	global_load_lds_dwordx4 v[222:223], off
	s_mov_b32 m0, s51
	s_nop 0
	global_load_lds_dwordx4 v[224:225], off
	s_waitcnt vmcnt(8)
	s_waitcnt lgkmcnt(0)
	s_barrier
	s_waitcnt lgkmcnt(0)
	v_mfma_f32_16x16x32_bf16 v[94:97], v[130:133], v[162:165], v[94:97]
	v_mfma_f32_16x16x32_bf16 v[90:93], v[138:141], v[162:165], v[90:93]
	v_mfma_f32_16x16x32_bf16 v[86:89], v[130:133], v[186:189], v[86:89]
	v_mfma_f32_16x16x32_bf16 v[82:85], v[138:141], v[186:189], v[82:85]
	v_mfma_f32_16x16x32_bf16 v[78:81], v[130:133], v[194:197], v[78:81]
	v_mfma_f32_16x16x32_bf16 v[74:77], v[138:141], v[194:197], v[74:77]
	v_mfma_f32_16x16x32_bf16 v[58:61], v[130:133], v[202:205], v[58:61]
	v_mfma_f32_16x16x32_bf16 v[50:53], v[138:141], v[202:205], v[50:53]
	v_mfma_f32_16x16x32_bf16 v[94:97], v[134:137], v[166:169], v[94:97]
	v_mfma_f32_16x16x32_bf16 v[90:93], v[142:145], v[166:169], v[90:93]
	v_mfma_f32_16x16x32_bf16 v[86:89], v[134:137], v[190:193], v[86:89]
	v_mfma_f32_16x16x32_bf16 v[82:85], v[142:145], v[190:193], v[82:85]
	v_mfma_f32_16x16x32_bf16 v[78:81], v[134:137], v[198:201], v[78:81]
	v_mfma_f32_16x16x32_bf16 v[74:77], v[142:145], v[198:201], v[74:77]
	v_mfma_f32_16x16x32_bf16 v[58:61], v[134:137], v[214:217], v[58:61]
	v_mfma_f32_16x16x32_bf16 v[50:53], v[142:145], v[214:217], v[50:53]
	v_mfma_f32_16x16x32_bf16 v[30:33], v[146:149], v[162:165], v[30:33]
	v_mfma_f32_16x16x32_bf16 v[26:29], v[154:157], v[162:165], v[26:29]
	v_mfma_f32_16x16x32_bf16 v[22:25], v[146:149], v[186:189], v[22:25]
	v_mfma_f32_16x16x32_bf16 v[18:21], v[154:157], v[186:189], v[18:21]
	v_mfma_f32_16x16x32_bf16 v[14:17], v[146:149], v[194:197], v[14:17]
	v_mfma_f32_16x16x32_bf16 v[10:13], v[154:157], v[194:197], v[10:13]
	v_mfma_f32_16x16x32_bf16 v[6:9], v[146:149], v[202:205], v[6:9]
	v_mfma_f32_16x16x32_bf16 v[2:5], v[154:157], v[202:205], v[2:5]
	v_mfma_f32_16x16x32_bf16 v[30:33], v[150:153], v[166:169], v[30:33]
	v_mfma_f32_16x16x32_bf16 v[26:29], v[158:161], v[166:169], v[26:29]
	v_mfma_f32_16x16x32_bf16 v[22:25], v[150:153], v[190:193], v[22:25]
	v_mfma_f32_16x16x32_bf16 v[18:21], v[158:161], v[190:193], v[18:21]
	v_mfma_f32_16x16x32_bf16 v[14:17], v[150:153], v[198:201], v[14:17]
	v_mfma_f32_16x16x32_bf16 v[10:13], v[158:161], v[198:201], v[10:13]
	v_mfma_f32_16x16x32_bf16 v[6:9], v[150:153], v[214:217], v[6:9]
	v_mfma_f32_16x16x32_bf16 v[2:5], v[158:161], v[214:217], v[2:5]
	s_barrier
	s_add_i32 s78, 0, 0x18000
	s_add_i32 s79, 0, 0x1c000
	v_add_u32_e32 v142, s78, v208
	v_add_u32_e32 v158, s79, v208
	ds_read_b128 v[130:133], v142
	ds_read_b128 v[134:137], v142 offset:1024
	ds_read_b128 v[138:141], v142 offset:2048
	ds_read_b128 v[142:145], v142 offset:3072
	ds_read_b128 v[146:149], v158
	ds_read_b128 v[150:153], v158 offset:1024
	ds_read_b128 v[154:157], v158 offset:2048
	ds_read_b128 v[158:161], v158 offset:3072
	s_add_u32 s42, s42, 0xb0000
	s_addc_u32 s43, s43, 0
	s_mov_b32 m0, s52
	v_lshl_add_u64 v[226:227], s[42:43], 0, v[170:171]
	ds_read_b128 v[162:165], v212 offset:32768
	ds_read_b128 v[166:169], v212 offset:33792
	ds_read_b128 v[186:189], v212 offset:34816
	ds_read_b128 v[190:193], v212 offset:35840
	ds_read_b128 v[194:197], v212 offset:36864
	ds_read_b128 v[198:201], v212 offset:37888
	ds_read_b128 v[202:205], v212 offset:38912
	ds_read_b128 v[214:217], v212 offset:39936
	global_load_lds_dwordx4 v[226:227], off
	v_lshl_add_u64 v[226:227], s[42:43], 0, v[174:175]
	s_mov_b32 m0, s53
	s_nop 0
	global_load_lds_dwordx4 v[226:227], off
	s_waitcnt vmcnt(8)
	s_waitcnt lgkmcnt(0)
	s_barrier
	s_waitcnt lgkmcnt(0)
	v_mfma_f32_16x16x32_bf16 v[126:129], v[130:133], v[162:165], v[126:129]
	v_mfma_f32_16x16x32_bf16 v[122:125], v[138:141], v[162:165], v[122:125]
	v_mfma_f32_16x16x32_bf16 v[118:121], v[130:133], v[186:189], v[118:121]
	v_mfma_f32_16x16x32_bf16 v[114:117], v[138:141], v[186:189], v[114:117]
	v_mfma_f32_16x16x32_bf16 v[110:113], v[130:133], v[194:197], v[110:113]
	v_mfma_f32_16x16x32_bf16 v[106:109], v[138:141], v[194:197], v[106:109]
	v_mfma_f32_16x16x32_bf16 v[102:105], v[130:133], v[202:205], v[102:105]
	v_mfma_f32_16x16x32_bf16 v[98:101], v[138:141], v[202:205], v[98:101]
	v_mfma_f32_16x16x32_bf16 v[126:129], v[134:137], v[166:169], v[126:129]
	v_mfma_f32_16x16x32_bf16 v[122:125], v[142:145], v[166:169], v[122:125]
	v_mfma_f32_16x16x32_bf16 v[118:121], v[134:137], v[190:193], v[118:121]
	v_mfma_f32_16x16x32_bf16 v[114:117], v[142:145], v[190:193], v[114:117]
	v_mfma_f32_16x16x32_bf16 v[110:113], v[134:137], v[198:201], v[110:113]
	v_mfma_f32_16x16x32_bf16 v[106:109], v[142:145], v[198:201], v[106:109]
	v_mfma_f32_16x16x32_bf16 v[102:105], v[134:137], v[214:217], v[102:105]
	v_mfma_f32_16x16x32_bf16 v[98:101], v[142:145], v[214:217], v[98:101]
	v_mfma_f32_16x16x32_bf16 v[70:73], v[146:149], v[162:165], v[70:73]
	v_mfma_f32_16x16x32_bf16 v[66:69], v[154:157], v[162:165], v[66:69]
	v_mfma_f32_16x16x32_bf16 v[62:65], v[146:149], v[186:189], v[62:65]
	v_mfma_f32_16x16x32_bf16 v[54:57], v[154:157], v[186:189], v[54:57]
	v_mfma_f32_16x16x32_bf16 v[46:49], v[146:149], v[194:197], v[46:49]
	v_mfma_f32_16x16x32_bf16 v[42:45], v[154:157], v[194:197], v[42:45]
	v_mfma_f32_16x16x32_bf16 v[38:41], v[146:149], v[202:205], v[38:41]
	v_mfma_f32_16x16x32_bf16 v[34:37], v[154:157], v[202:205], v[34:37]
	v_mfma_f32_16x16x32_bf16 v[70:73], v[150:153], v[166:169], v[70:73]
	v_mfma_f32_16x16x32_bf16 v[66:69], v[158:161], v[166:169], v[66:69]
	v_mfma_f32_16x16x32_bf16 v[62:65], v[150:153], v[190:193], v[62:65]
	v_mfma_f32_16x16x32_bf16 v[54:57], v[158:161], v[190:193], v[54:57]
	v_mfma_f32_16x16x32_bf16 v[46:49], v[150:153], v[198:201], v[46:49]
	v_mfma_f32_16x16x32_bf16 v[42:45], v[158:161], v[198:201], v[42:45]
	v_mfma_f32_16x16x32_bf16 v[38:41], v[150:153], v[214:217], v[38:41]
	v_mfma_f32_16x16x32_bf16 v[34:37], v[158:161], v[214:217], v[34:37]
	s_barrier
	s_add_i32 s42, s78, s48
	v_lshl_add_u64 v[218:219], v[218:219], 0, s[14:15]
	s_mov_b32 m0, s42
	ds_read_b128 v[162:165], v212 offset:49152
	ds_read_b128 v[166:169], v212 offset:50176
	ds_read_b128 v[186:189], v212 offset:51200
	ds_read_b128 v[190:193], v212 offset:52224
	ds_read_b128 v[194:197], v212 offset:53248
	ds_read_b128 v[198:201], v212 offset:54272
	ds_read_b128 v[202:205], v212 offset:55296
	ds_read_b128 v[214:217], v212 offset:56320
	global_load_lds_dwordx4 v[218:219], off
	s_add_i32 m0, s42, 0x2000
	s_add_u32 s40, s40, 0xb0080
	v_lshl_add_u64 v[218:219], v[220:221], 0, s[14:15]
	s_addc_u32 s41, s41, 0
	s_add_i32 s42, s79, s48
	global_load_lds_dwordx4 v[218:219], off
	v_lshl_add_u64 v[218:219], s[40:41], 0, v[172:173]
	s_mov_b32 m0, s42
	s_nop 0
	global_load_lds_dwordx4 v[218:219], off
	v_lshl_add_u64 v[218:219], s[40:41], 0, v[176:177]
	s_add_i32 m0, s42, 0x2000
	s_nop 0
	global_load_lds_dwordx4 v[218:219], off
	v_lshl_add_u64 v[218:219], v[222:223], 0, s[14:15]
	s_mov_b32 m0, s58
	s_nop 0
	global_load_lds_dwordx4 v[218:219], off
	v_lshl_add_u64 v[218:219], v[224:225], 0, s[14:15]
	s_mov_b32 m0, s59
	s_nop 0
	global_load_lds_dwordx4 v[218:219], off
	s_waitcnt vmcnt(8)
	s_waitcnt lgkmcnt(0)
	s_barrier
	s_waitcnt lgkmcnt(0)
	v_mfma_f32_16x16x32_bf16 v[94:97], v[130:133], v[162:165], v[94:97]
	v_mfma_f32_16x16x32_bf16 v[90:93], v[138:141], v[162:165], v[90:93]
	v_mfma_f32_16x16x32_bf16 v[86:89], v[130:133], v[186:189], v[86:89]
	v_mfma_f32_16x16x32_bf16 v[82:85], v[138:141], v[186:189], v[82:85]
	v_mfma_f32_16x16x32_bf16 v[78:81], v[130:133], v[194:197], v[78:81]
	v_mfma_f32_16x16x32_bf16 v[74:77], v[138:141], v[194:197], v[74:77]
	v_mfma_f32_16x16x32_bf16 v[58:61], v[130:133], v[202:205], v[58:61]
	v_mfma_f32_16x16x32_bf16 v[50:53], v[138:141], v[202:205], v[50:53]
	v_mfma_f32_16x16x32_bf16 v[94:97], v[134:137], v[166:169], v[94:97]
	v_mfma_f32_16x16x32_bf16 v[90:93], v[142:145], v[166:169], v[90:93]
	v_mfma_f32_16x16x32_bf16 v[86:89], v[134:137], v[190:193], v[86:89]
	v_mfma_f32_16x16x32_bf16 v[82:85], v[142:145], v[190:193], v[82:85]
	v_mfma_f32_16x16x32_bf16 v[78:81], v[134:137], v[198:201], v[78:81]
	v_mfma_f32_16x16x32_bf16 v[74:77], v[142:145], v[198:201], v[74:77]
	v_mfma_f32_16x16x32_bf16 v[58:61], v[134:137], v[214:217], v[58:61]
	v_mfma_f32_16x16x32_bf16 v[50:53], v[142:145], v[214:217], v[50:53]
	v_mfma_f32_16x16x32_bf16 v[30:33], v[146:149], v[162:165], v[30:33]
	v_mfma_f32_16x16x32_bf16 v[26:29], v[154:157], v[162:165], v[26:29]
	v_mfma_f32_16x16x32_bf16 v[22:25], v[146:149], v[186:189], v[22:25]
	v_mfma_f32_16x16x32_bf16 v[18:21], v[154:157], v[186:189], v[18:21]
	v_mfma_f32_16x16x32_bf16 v[14:17], v[146:149], v[194:197], v[14:17]
	v_mfma_f32_16x16x32_bf16 v[10:13], v[154:157], v[194:197], v[10:13]
	v_mfma_f32_16x16x32_bf16 v[6:9], v[146:149], v[202:205], v[6:9]
	v_mfma_f32_16x16x32_bf16 v[2:5], v[154:157], v[202:205], v[2:5]
	v_mfma_f32_16x16x32_bf16 v[30:33], v[150:153], v[166:169], v[30:33]
	v_mfma_f32_16x16x32_bf16 v[26:29], v[158:161], v[166:169], v[26:29]
	v_mfma_f32_16x16x32_bf16 v[22:25], v[150:153], v[190:193], v[22:25]
	v_mfma_f32_16x16x32_bf16 v[18:21], v[158:161], v[190:193], v[18:21]
	v_mfma_f32_16x16x32_bf16 v[14:17], v[150:153], v[198:201], v[14:17]
	v_mfma_f32_16x16x32_bf16 v[10:13], v[158:161], v[198:201], v[10:13]
	v_mfma_f32_16x16x32_bf16 v[6:9], v[150:153], v[214:217], v[6:9]
	v_mfma_f32_16x16x32_bf16 v[2:5], v[158:161], v[214:217], v[2:5]
	s_barrier
	s_add_i32 s77, s77, 2
	s_add_u32 s38, s38, 0x100
	s_addc_u32 s39, s39, 0
	s_add_u32 s44, s44, 0x100
	s_addc_u32 s45, s45, 0
	s_cmp_gt_u32 s77, 41
	s_cbranch_scc0 .LBB0_1541
	s_setprio 0
	s_and_b64 vcc, exec, s[16:17]
	s_cbranch_vccz .LBB0_1544
	s_barrier
